# nt hint on the attention epilogues' read-once SiLU-gate loads (they were prefetched into L2; the hint keeps them from displacing reused lines); otherwise identical to v118
# speedup vs baseline: 1.0072x; 1.0049x over previous
.LBB0_128:
	v_exp_f32_e32 v0, v66
	v_exp_f32_e32 v67, v67
	v_exp_f32_e32 v68, v68
	v_exp_f32_e32 v69, v69
	v_add_f32_e32 v66, 0, v0
	v_exp_f32_e32 v70, v70
	v_add_f32_e32 v66, v67, v66
	v_exp_f32_e32 v71, v71
	v_add_f32_e32 v66, v68, v66
	v_exp_f32_e32 v72, v72
	v_add_f32_e32 v66, v69, v66
	v_exp_f32_e32 v98, v73
	v_add_f32_e32 v66, v70, v66
	v_exp_f32_e32 v74, v74
	v_add_f32_e32 v66, v71, v66
	v_exp_f32_e32 v75, v75
	v_add_f32_e32 v66, v72, v66
	v_exp_f32_e32 v76, v76
	v_add_f32_e32 v66, v98, v66
	v_exp_f32_e32 v77, v77
	v_add_f32_e32 v66, v74, v66
	v_exp_f32_e32 v78, v78
	v_add_f32_e32 v66, v75, v66
	v_exp_f32_e32 v79, v79
	v_add_f32_e32 v66, v76, v66
	v_exp_f32_e32 v80, v80
	v_add_f32_e32 v66, v77, v66
	v_exp_f32_e32 v81, v81
	v_add_f32_e32 v66, v78, v66
	v_add_f32_e32 v66, v79, v66
	v_add_f32_e32 v66, v80, v66
	v_add_f32_e32 v66, v81, v66
	v_add_f32_e32 v73, v166, v66
	v_cvt_pk_bf16_f32 v66, v0, v67
	v_cvt_pk_bf16_f32 v67, v68, v69
	v_cvt_pk_bf16_f32 v68, v70, v71
	v_cvt_pk_bf16_f32 v69, v72, v98
	s_waitcnt vmcnt(0)
	s_barrier
	v_mbcnt_lo_u32_b32 v116, -1, 0
	v_mbcnt_hi_u32_b32 v116, -1, v116
	v_mov_b32_e32 v148, s77
	v_lshlrev_b32_e32 v148, 6, v148
	v_and_b32_e32 v117, 31, v116
	v_lshrrev_b32_e32 v149, 5, v116
	v_lshl_add_u32 v122, v117, 7, v148
	v_and_b32_e32 v117, 7, v117
	v_sub_u32_e32 v118, 1, v149
	v_xor_b32_e32 v118, v118, v117
	v_lshl_add_u32 v118, v118, 4, v122
	v_sub_u32_e32 v119, 3, v149
	v_xor_b32_e32 v119, v119, v117
	v_lshl_add_u32 v119, v119, 4, v122
	v_sub_u32_e32 v120, 5, v149
	v_xor_b32_e32 v120, v120, v117
	v_lshl_add_u32 v120, v120, 4, v122
	v_sub_u32_e32 v121, 7, v149
	v_xor_b32_e32 v121, v121, v117
	v_lshl_add_u32 v121, v121, 4, v122
	v_lshrrev_b32_e32 v117, 3, v116
	v_and_b32_e32 v149, 7, v116
	v_lshl_add_u32 v122, v117, 7, v148
	v_xor_b32_e32 v148, v149, v117
	v_lshl_add_u32 v122, v148, 4, v122
	v_mul_u32_u24_e32 v144, 0x880, v117
	v_lshl_add_u32 v144, v149, 4, v144
	v_add_u32_e32 v145, 0x4400, v144
	v_add_u32_e32 v146, 0x8800, v144
	v_add_u32_e32 v147, 0xcc00, v144
	v_mbcnt_lo_u32_b32 v108, -1, 0
	v_mbcnt_hi_u32_b32 v108, -1, v108
	v_cmp_gt_u32_e32 vcc, 32, v108
	s_nop 1
	v_cndmask_b32_e64 v109, -1, 0, vcc
	v_cndmask_b32_e64 v108, -8, 16, vcc
	v_mfma_f32_32x32x16_bf16 v[18:33], v[82:85], v[66:69], v[18:33]
	v_mbcnt_lo_u32_b32 v0, -1, 0
	v_mbcnt_hi_u32_b32 v0, -1, v0
	s_movk_i32 s0, 0x100
	s_movk_i32 s5, 0xf3c0
	s_mov_b64 s[18:19], 0x44012c0
	s_mov_b32 s8, 0x4401000
	v_mfma_f32_32x32x16_bf16 v[2:17], v[86:89], v[66:69], v[2:17]
	v_cvt_pk_bf16_f32 v66, v74, v75
	v_cvt_pk_bf16_f32 v67, v76, v77
	v_cvt_pk_bf16_f32 v68, v78, v79
	v_cvt_pk_bf16_f32 v69, v80, v81
	s_nop 1
	v_mfma_f32_32x32x16_bf16 v[18:33], v[90:93], v[66:69], v[18:33]
	v_mfma_f32_32x32x16_bf16 v[2:17], v[94:97], v[66:69], v[2:17]
	v_add_u32_e32 v66, s77, v0
	v_cmp_gt_u32_e32 vcc, s0, v66
	v_mov_b32_e32 v68, s30
	v_mov_b32_e32 v69, s28
	v_cndmask_b32_e32 v68, v68, v69, vcc
	v_and_b32_e32 v66, 0xc0, v66
	v_and_b32_e32 v67, 31, v0
	v_lshl_or_b32 v66, v68, 8, v66
	v_or3_b32 v86, v66, v67, s40
	v_mov_b32_e32 v66, v142
	s_nop 1
	v_permlane32_swap_b32_e32 v142, v66
	v_add_f32_e32 v72, v142, v66
	v_mov_b64_e32 v[66:67], s[74:75]
	v_mad_u64_u32 v[66:67], s[0:1], v86, s4, v[66:67]
	v_mov_b32_e32 v68, 0x14c0
	v_mad_i32_i24 v67, s41, v68, v67
	s_lshl_b32 s28, s31, 1
	v_lshrrev_b32_e32 v0, 2, v0
	v_lshl_add_u64 v[68:69], v[66:67], 0, s[28:29]
	v_and_b32_e32 v0, 8, v0
	v_lshl_add_u64 v[68:69], v[68:69], 0, v[0:1]
	v_mad_u64_u32 v[88:89], s[0:1], v86, s5, v[66:67]
	v_mov_b32_e32 v94, 0xfffff3c0
	v_lshl_add_u64 v[90:91], v[68:69], 0, s[18:19]
	v_add_co_u32_e32 v68, vcc, s8, v68
	v_mad_i32_i24 v70, s41, v94, v89
	s_nop 0
	v_addc_co_u32_e32 v69, vcc, 0, v69, vcc
	v_sub_u32_e32 v89, v70, v86
	v_lshl_add_u64 v[114:115], v[90:91], 0, v[108:109]
	global_load_dwordx4 v[170:173], v[114:115], off nt
	global_load_dwordx4 v[174:177], v[114:115], off offset:32 nt
	global_load_dwordx4 v[178:181], v[114:115], off offset:64 nt
	global_load_dwordx4 v[182:185], v[114:115], off offset:96 nt
	v_rcp_f32_e32 v72, v72
	v_lshl_add_u64 v[88:89], v[88:89], 0, s[28:29]
	s_mov_b64 s[0:1], 0x29800
	v_pk_mul_f32 v[50:51], v[50:51], v[72:73] op_sel_hi:[1,0]
	v_pk_mul_f32 v[52:53], v[52:53], v[72:73] op_sel_hi:[1,0]
	v_pk_mul_f32 v[54:55], v[54:55], v[72:73] op_sel_hi:[1,0]
	v_pk_mul_f32 v[56:57], v[56:57], v[72:73] op_sel_hi:[1,0]
	v_pk_mul_f32 v[34:35], v[34:35], v[72:73] op_sel_hi:[1,0]
	v_pk_mul_f32 v[36:37], v[36:37], v[72:73] op_sel_hi:[1,0]
	v_pk_mul_f32 v[38:39], v[38:39], v[72:73] op_sel_hi:[1,0]
	v_pk_mul_f32 v[40:41], v[40:41], v[72:73] op_sel_hi:[1,0]
	s_waitcnt vmcnt(3)
	v_permlane32_swap_b32_e32 v170, v172
	v_permlane32_swap_b32_e32 v171, v173
	v_mov_b32_e32 v82, v170
	v_mov_b32_e32 v83, v171
	v_mov_b32_e32 v84, v172
	v_mov_b32_e32 v85, v173
	v_lshlrev_b32_e32 v90, 16, v84
	v_and_b32_e32 v91, 0xffff0000, v84
	v_mul_f32_e32 v84, 0xbfb8aa3b, v90
	v_exp_f32_e32 v84, v84
	s_nop 0
	v_add_f32_e32 v84, 1.0, v84
	v_rcp_f32_e32 v92, v84
	v_mul_f32_e32 v84, 0xbfb8aa3b, v91
	v_exp_f32_e32 v84, v84
	s_nop 0
	v_add_f32_e32 v84, 1.0, v84
	v_rcp_f32_e32 v93, v84
	v_lshlrev_b32_e32 v84, 16, v85
	v_mul_f32_e32 v87, 0xbfb8aa3b, v84
	v_exp_f32_e32 v87, v87
	v_pk_mul_f32 v[90:91], v[92:93], v[90:91]
	v_and_b32_e32 v85, 0xffff0000, v85
	v_pk_mul_f32 v[50:51], v[50:51], v[90:91]
	v_add_f32_e32 v87, 1.0, v87
	v_rcp_f32_e32 v90, v87
	v_mul_f32_e32 v87, 0xbfb8aa3b, v85
	v_exp_f32_e32 v87, v87
	s_nop 0
	v_add_f32_e32 v87, 1.0, v87
	v_rcp_f32_e32 v91, v87
	s_nop 0
	v_pk_mul_f32 v[84:85], v[90:91], v[84:85]
	s_nop 0
	v_pk_mul_f32 v[52:53], v[52:53], v[84:85]
	v_cvt_pk_bf16_f32 v84, v50, v51
	v_cvt_pk_bf16_f32 v85, v52, v53
	s_waitcnt vmcnt(3)
	v_lshlrev_b32_e32 v52, 16, v82
	v_and_b32_e32 v53, 0xffff0000, v82
	v_mul_f32_e32 v82, 0xbfb8aa3b, v52
	v_exp_f32_e32 v82, v82
	v_lshl_add_u64 v[50:51], v[88:89], 0, v[0:1]
	v_mov_b32_e32 v106, v84
	v_mov_b32_e32 v107, v85
	v_add_f32_e32 v82, 1.0, v82
	v_rcp_f32_e32 v84, v82
	v_mul_f32_e32 v82, 0xbfb8aa3b, v53
	v_exp_f32_e32 v82, v82
	s_nop 0
	v_add_f32_e32 v82, 1.0, v82
	v_rcp_f32_e32 v85, v82
	s_nop 0
	v_pk_mul_f32 v[52:53], v[84:85], v[52:53]
	s_nop 0
	v_pk_mul_f32 v[52:53], v[54:55], v[52:53]
	v_lshlrev_b32_e32 v54, 16, v83
	v_and_b32_e32 v55, 0xffff0000, v83
	v_mul_f32_e32 v82, 0xbfb8aa3b, v54
	v_mul_f32_e32 v83, 0xbfb8aa3b, v55
	v_exp_f32_e32 v82, v82
	v_exp_f32_e32 v83, v83
	v_cvt_pk_bf16_f32 v52, v52, v53
	v_add_f32_e32 v82, 1.0, v82
	v_add_f32_e32 v83, 1.0, v83
	v_rcp_f32_e32 v82, v82
	v_rcp_f32_e32 v83, v83
	s_nop 0
	v_pk_mul_f32 v[54:55], v[82:83], v[54:55]
	s_nop 0
	v_pk_mul_f32 v[54:55], v[56:57], v[54:55]
	v_pk_mul_f32 v[56:57], v[58:59], v[72:73] op_sel_hi:[1,0]
	v_cvt_pk_bf16_f32 v53, v54, v55
	v_readfirstlane_b32 s98, v50
	v_readfirstlane_b32 s99, v51
	v_mov_b32_e32 v104, v52
	v_mov_b32_e32 v105, v53
	s_nop 1
	v_permlane32_swap_b32_e32 v104, v106
	v_permlane32_swap_b32_e32 v105, v107
	ds_write_b128 v118, v[104:107]
	s_waitcnt vmcnt(2)
	v_permlane32_swap_b32_e32 v174, v176
	v_permlane32_swap_b32_e32 v175, v177
	v_mov_b32_e32 v78, v174
	v_mov_b32_e32 v79, v175
	v_mov_b32_e32 v80, v176
	v_mov_b32_e32 v81, v177
	v_lshlrev_b32_e32 v52, 16, v80
	v_and_b32_e32 v53, 0xffff0000, v80
	v_mul_f32_e32 v54, 0xbfb8aa3b, v52
	v_mul_f32_e32 v55, 0xbfb8aa3b, v53
	v_exp_f32_e32 v54, v54
	v_exp_f32_e32 v55, v55
	v_pk_mul_f32 v[58:59], v[60:61], v[72:73] op_sel_hi:[1,0]
	v_add_f32_e32 v54, 1.0, v54
	v_add_f32_e32 v55, 1.0, v55
	v_rcp_f32_e32 v54, v54
	v_rcp_f32_e32 v55, v55
	s_nop 0
	v_pk_mul_f32 v[52:53], v[54:55], v[52:53]
	v_lshlrev_b32_e32 v54, 16, v81
	v_and_b32_e32 v55, 0xffff0000, v81
	v_pk_mul_f32 v[52:53], v[56:57], v[52:53]
	v_mul_f32_e32 v56, 0xbfb8aa3b, v54
	v_mul_f32_e32 v57, 0xbfb8aa3b, v55
	v_exp_f32_e32 v56, v56
	v_exp_f32_e32 v57, v57
	v_cvt_pk_bf16_f32 v52, v52, v53
	v_add_f32_e32 v56, 1.0, v56
	v_add_f32_e32 v57, 1.0, v57
	v_rcp_f32_e32 v56, v56
	v_rcp_f32_e32 v57, v57
	s_nop 0
	v_pk_mul_f32 v[54:55], v[56:57], v[54:55]
	s_nop 0
	v_pk_mul_f32 v[54:55], v[58:59], v[54:55]
	v_pk_mul_f32 v[56:57], v[62:63], v[72:73] op_sel_hi:[1,0]
	v_cvt_pk_bf16_f32 v53, v54, v55
	v_mov_b32_e32 v106, v52
	v_mov_b32_e32 v107, v53
	s_waitcnt vmcnt(2)
	v_lshlrev_b32_e32 v52, 16, v78
	v_and_b32_e32 v53, 0xffff0000, v78
	v_mul_f32_e32 v54, 0xbfb8aa3b, v52
	v_mul_f32_e32 v55, 0xbfb8aa3b, v53
	v_exp_f32_e32 v54, v54
	v_exp_f32_e32 v55, v55
	v_pk_mul_f32 v[58:59], v[64:65], v[72:73] op_sel_hi:[1,0]
	v_add_f32_e32 v54, 1.0, v54
	v_add_f32_e32 v55, 1.0, v55
	v_rcp_f32_e32 v54, v54
	v_rcp_f32_e32 v55, v55
	s_nop 0
	v_pk_mul_f32 v[52:53], v[54:55], v[52:53]
	v_lshlrev_b32_e32 v54, 16, v79
	v_and_b32_e32 v55, 0xffff0000, v79
	v_pk_mul_f32 v[52:53], v[56:57], v[52:53]
	v_mul_f32_e32 v56, 0xbfb8aa3b, v54
	v_mul_f32_e32 v57, 0xbfb8aa3b, v55
	v_exp_f32_e32 v56, v56
	v_exp_f32_e32 v57, v57
	v_cvt_pk_bf16_f32 v52, v52, v53
	v_add_f32_e32 v56, 1.0, v56
	v_add_f32_e32 v57, 1.0, v57
	v_rcp_f32_e32 v56, v56
	v_rcp_f32_e32 v57, v57
	s_nop 0
	v_pk_mul_f32 v[54:55], v[56:57], v[54:55]
	s_nop 0
	v_pk_mul_f32 v[54:55], v[58:59], v[54:55]
	s_nop 0
	v_cvt_pk_bf16_f32 v53, v54, v55
	v_mov_b32_e32 v104, v52
	v_mov_b32_e32 v105, v53
	s_nop 1
	v_permlane32_swap_b32_e32 v104, v106
	v_permlane32_swap_b32_e32 v105, v107
	ds_write_b128 v119, v[104:107]
	s_waitcnt vmcnt(1)
	v_permlane32_swap_b32_e32 v178, v180
	v_permlane32_swap_b32_e32 v179, v181
	v_mov_b32_e32 v74, v178
	v_mov_b32_e32 v75, v179
	v_mov_b32_e32 v76, v180
	v_mov_b32_e32 v77, v181
	v_lshlrev_b32_e32 v52, 16, v76
	v_and_b32_e32 v53, 0xffff0000, v76
	v_mul_f32_e32 v54, 0xbfb8aa3b, v52
	v_mul_f32_e32 v55, 0xbfb8aa3b, v53
	v_exp_f32_e32 v54, v54
	v_exp_f32_e32 v55, v55
	v_add_f32_e32 v54, 1.0, v54
	v_add_f32_e32 v55, 1.0, v55
	v_rcp_f32_e32 v54, v54
	v_rcp_f32_e32 v55, v55
	s_nop 0
	v_pk_mul_f32 v[52:53], v[54:55], v[52:53]
	s_nop 0
	v_pk_mul_f32 v[34:35], v[34:35], v[52:53]
	v_lshlrev_b32_e32 v52, 16, v77
	v_and_b32_e32 v53, 0xffff0000, v77
	v_mul_f32_e32 v54, 0xbfb8aa3b, v52
	v_mul_f32_e32 v55, 0xbfb8aa3b, v53
	v_exp_f32_e32 v54, v54
	v_exp_f32_e32 v55, v55
	v_cvt_pk_bf16_f32 v34, v34, v35
	v_add_f32_e32 v54, 1.0, v54
	v_add_f32_e32 v55, 1.0, v55
	v_rcp_f32_e32 v54, v54
	v_rcp_f32_e32 v55, v55
	s_nop 0
	v_pk_mul_f32 v[52:53], v[54:55], v[52:53]
	s_nop 0
	v_pk_mul_f32 v[36:37], v[36:37], v[52:53]
	s_nop 0
	v_cvt_pk_bf16_f32 v35, v36, v37
	v_mov_b32_e32 v106, v34
	v_mov_b32_e32 v107, v35
	s_waitcnt vmcnt(1)
	v_lshlrev_b32_e32 v34, 16, v74
	v_and_b32_e32 v35, 0xffff0000, v74
	v_mul_f32_e32 v36, 0xbfb8aa3b, v34
	v_mul_f32_e32 v37, 0xbfb8aa3b, v35
	v_exp_f32_e32 v36, v36
	v_exp_f32_e32 v37, v37
	v_add_f32_e32 v36, 1.0, v36
	v_add_f32_e32 v37, 1.0, v37
	v_rcp_f32_e32 v36, v36
	v_rcp_f32_e32 v37, v37
	s_nop 0
	v_pk_mul_f32 v[34:35], v[36:37], v[34:35]
	v_lshlrev_b32_e32 v36, 16, v75
	v_and_b32_e32 v37, 0xffff0000, v75
	v_pk_mul_f32 v[34:35], v[38:39], v[34:35]
	v_mul_f32_e32 v38, 0xbfb8aa3b, v36
	v_mul_f32_e32 v39, 0xbfb8aa3b, v37
	v_exp_f32_e32 v38, v38
	v_exp_f32_e32 v39, v39
	v_cvt_pk_bf16_f32 v34, v34, v35
	v_add_f32_e32 v38, 1.0, v38
	v_add_f32_e32 v39, 1.0, v39
	v_rcp_f32_e32 v38, v38
	v_rcp_f32_e32 v39, v39
	s_nop 0
	v_pk_mul_f32 v[36:37], v[38:39], v[36:37]
	s_nop 0
	v_pk_mul_f32 v[36:37], v[40:41], v[36:37]
	v_pk_mul_f32 v[38:39], v[42:43], v[72:73] op_sel_hi:[1,0]
	v_cvt_pk_bf16_f32 v35, v36, v37
	v_mov_b32_e32 v104, v34
	v_mov_b32_e32 v105, v35
	s_nop 1
	v_permlane32_swap_b32_e32 v104, v106
	v_permlane32_swap_b32_e32 v105, v107
	ds_write_b128 v120, v[104:107]
	s_waitcnt vmcnt(0)
	v_permlane32_swap_b32_e32 v182, v184
	v_permlane32_swap_b32_e32 v183, v185
	v_mov_b32_e32 v68, v182
	v_mov_b32_e32 v69, v183
	v_mov_b32_e32 v70, v184
	v_mov_b32_e32 v71, v185
	v_lshlrev_b32_e32 v34, 16, v70
	v_and_b32_e32 v35, 0xffff0000, v70
	v_mul_f32_e32 v36, 0xbfb8aa3b, v34
	v_mul_f32_e32 v37, 0xbfb8aa3b, v35
	v_exp_f32_e32 v36, v36
	v_exp_f32_e32 v37, v37
	v_pk_mul_f32 v[40:41], v[44:45], v[72:73] op_sel_hi:[1,0]
	v_add_f32_e32 v36, 1.0, v36
	v_add_f32_e32 v37, 1.0, v37
	v_rcp_f32_e32 v36, v36
	v_rcp_f32_e32 v37, v37
	s_nop 0
	v_pk_mul_f32 v[34:35], v[36:37], v[34:35]
	v_lshlrev_b32_e32 v36, 16, v71
	v_and_b32_e32 v37, 0xffff0000, v71
	v_pk_mul_f32 v[34:35], v[38:39], v[34:35]
	v_mul_f32_e32 v38, 0xbfb8aa3b, v36
	v_mul_f32_e32 v39, 0xbfb8aa3b, v37
	v_exp_f32_e32 v38, v38
	v_exp_f32_e32 v39, v39
	v_cvt_pk_bf16_f32 v34, v34, v35
	v_add_f32_e32 v38, 1.0, v38
	v_add_f32_e32 v39, 1.0, v39
	v_rcp_f32_e32 v38, v38
	v_rcp_f32_e32 v39, v39
	s_nop 0
	v_pk_mul_f32 v[36:37], v[38:39], v[36:37]
	s_nop 0
	v_pk_mul_f32 v[36:37], v[40:41], v[36:37]
	v_pk_mul_f32 v[38:39], v[46:47], v[72:73] op_sel_hi:[1,0]
	v_cvt_pk_bf16_f32 v35, v36, v37
	v_mov_b32_e32 v106, v34
	v_mov_b32_e32 v107, v35
	s_waitcnt vmcnt(0)
	v_lshlrev_b32_e32 v34, 16, v68
	v_and_b32_e32 v35, 0xffff0000, v68
	v_mul_f32_e32 v36, 0xbfb8aa3b, v34
	v_mul_f32_e32 v37, 0xbfb8aa3b, v35
	v_exp_f32_e32 v36, v36
	v_exp_f32_e32 v37, v37
	v_pk_mul_f32 v[40:41], v[48:49], v[72:73] op_sel_hi:[1,0]
	v_add_f32_e32 v36, 1.0, v36
	v_add_f32_e32 v37, 1.0, v37
	v_rcp_f32_e32 v36, v36
	v_rcp_f32_e32 v37, v37
	s_nop 0
	v_pk_mul_f32 v[34:35], v[36:37], v[34:35]
	v_lshlrev_b32_e32 v36, 16, v69
	v_and_b32_e32 v37, 0xffff0000, v69
	v_pk_mul_f32 v[34:35], v[38:39], v[34:35]
	v_mul_f32_e32 v38, 0xbfb8aa3b, v36
	v_mul_f32_e32 v39, 0xbfb8aa3b, v37
	v_exp_f32_e32 v38, v38
	v_exp_f32_e32 v39, v39
	v_cvt_pk_bf16_f32 v34, v34, v35
	v_add_f32_e32 v38, 1.0, v38
	v_add_f32_e32 v39, 1.0, v39
	v_rcp_f32_e32 v38, v38
	v_rcp_f32_e32 v39, v39
	s_nop 0
	v_pk_mul_f32 v[36:37], v[38:39], v[36:37]
	s_nop 0
	v_pk_mul_f32 v[36:37], v[40:41], v[36:37]
	v_or_b32_e32 v38, 32, v86
	v_cvt_pk_bf16_f32 v35, v36, v37
	v_mov_b32_e32 v104, v34
	v_mov_b32_e32 v105, v35
	s_nop 1
	v_permlane32_swap_b32_e32 v104, v106
	v_permlane32_swap_b32_e32 v105, v107
	ds_write_b128 v121, v[104:107]
	ds_read_b128 v[124:127], v122
	ds_read_b128 v[128:131], v122 offset:1024
	ds_read_b128 v[132:135], v122 offset:2048
	ds_read_b128 v[136:139], v122 offset:3072
	s_waitcnt lgkmcnt(3)
	global_store_dwordx4 v144, v[124:127], s[98:99] offset:1536 sc0 sc1
	s_waitcnt lgkmcnt(2)
	global_store_dwordx4 v145, v[128:131], s[98:99] offset:1536 sc0 sc1
	s_waitcnt lgkmcnt(1)
	global_store_dwordx4 v146, v[132:135], s[98:99] offset:1536 sc0 sc1
	s_waitcnt lgkmcnt(0)
	global_store_dwordx4 v147, v[136:139], s[98:99] offset:1536 sc0 sc1
	v_mov_b32_e32 v34, v73
	s_nop 1
	v_permlane32_swap_b32_e32 v73, v34
	v_add_f32_e32 v54, v73, v34
	v_lshl_add_u64 v[34:35], v[66:67], 0, s[0:1]
	v_lshl_add_u64 v[36:37], v[34:35], 0, s[28:29]
	v_mad_u64_u32 v[52:53], s[0:1], v38, s5, v[34:35]
	v_mad_i32_i24 v34, s41, v94, v53
	v_lshl_add_u64 v[36:37], v[36:37], 0, v[0:1]
	v_sub_u32_e32 v53, v34, v38
	v_lshl_add_u64 v[34:35], v[36:37], 0, s[18:19]
	v_add_co_u32_e32 v36, vcc, s8, v36
	v_lshl_add_u64 v[52:53], v[52:53], 0, s[28:29]
	s_nop 0
	v_addc_co_u32_e32 v37, vcc, 0, v37, vcc
	v_lshl_add_u64 v[116:117], v[34:35], 0, v[108:109]
	global_load_dwordx4 v[186:189], v[116:117], off nt
	global_load_dwordx4 v[190:193], v[116:117], off offset:32 nt
	global_load_dwordx4 v[194:197], v[116:117], off offset:64 nt
	global_load_dwordx4 v[198:201], v[116:117], off offset:96 nt
	v_rcp_f32_e32 v34, v54
	s_waitcnt vmcnt(3)
	v_permlane32_swap_b32_e32 v186, v188
	v_permlane32_swap_b32_e32 v187, v189
	v_mov_b32_e32 v48, v186
	v_mov_b32_e32 v49, v187
	v_mov_b32_e32 v50, v188
	v_mov_b32_e32 v51, v189
	v_lshlrev_b32_e32 v54, 16, v50
	v_mul_f32_e32 v35, 0xbfb8aa3b, v54
	v_exp_f32_e32 v35, v35
	v_and_b32_e32 v55, 0xffff0000, v50
	v_lshlrev_b32_e32 v50, 16, v51
	v_and_b32_e32 v51, 0xffff0000, v51
	v_add_f32_e32 v35, 1.0, v35
	v_rcp_f32_e32 v56, v35
	v_pk_mul_f32 v[18:19], v[18:19], v[34:35] op_sel_hi:[1,0]
	v_mul_f32_e32 v35, 0xbfb8aa3b, v55
	v_exp_f32_e32 v35, v35
	s_nop 0
	v_add_f32_e32 v35, 1.0, v35
	v_rcp_f32_e32 v57, v35
	v_mul_f32_e32 v35, 0xbfb8aa3b, v50
	v_exp_f32_e32 v35, v35
	v_pk_mul_f32 v[54:55], v[56:57], v[54:55]
	s_nop 0
	v_pk_mul_f32 v[18:19], v[18:19], v[54:55]
	v_add_f32_e32 v35, 1.0, v35
	v_rcp_f32_e32 v54, v35
	v_pk_mul_f32 v[20:21], v[20:21], v[34:35] op_sel_hi:[1,0]
	v_mul_f32_e32 v35, 0xbfb8aa3b, v51
	v_exp_f32_e32 v35, v35
	s_nop 0
	v_add_f32_e32 v35, 1.0, v35
	v_rcp_f32_e32 v55, v35
	v_pk_mul_f32 v[22:23], v[22:23], v[34:35] op_sel_hi:[1,0]
	v_pk_mul_f32 v[24:25], v[24:25], v[34:35] op_sel_hi:[1,0]
	v_pk_mul_f32 v[2:3], v[2:3], v[34:35] op_sel_hi:[1,0]
	v_pk_mul_f32 v[50:51], v[54:55], v[50:51]
	v_pk_mul_f32 v[4:5], v[4:5], v[34:35] op_sel_hi:[1,0]
	v_pk_mul_f32 v[20:21], v[20:21], v[50:51]
	v_cvt_pk_bf16_f32 v50, v18, v19
	v_cvt_pk_bf16_f32 v51, v20, v21
	s_waitcnt vmcnt(3)
	v_lshlrev_b32_e32 v20, 16, v48
	v_lshl_add_u64 v[18:19], v[52:53], 0, v[0:1]
	v_mul_f32_e32 v0, 0xbfb8aa3b, v20
	v_exp_f32_e32 v0, v0
	v_and_b32_e32 v21, 0xffff0000, v48
	v_mov_b32_e32 v106, v50
	v_mov_b32_e32 v107, v51
	v_pk_mul_f32 v[6:7], v[6:7], v[34:35] op_sel_hi:[1,0]
	v_add_f32_e32 v0, 1.0, v0
	v_rcp_f32_e32 v50, v0
	v_mul_f32_e32 v0, 0xbfb8aa3b, v21
	v_exp_f32_e32 v0, v0
	v_pk_mul_f32 v[8:9], v[8:9], v[34:35] op_sel_hi:[1,0]
	v_add_f32_e32 v0, 1.0, v0
	v_rcp_f32_e32 v51, v0
	s_nop 0
	v_pk_mul_f32 v[20:21], v[50:51], v[20:21]
	s_nop 0
	v_pk_mul_f32 v[20:21], v[22:23], v[20:21]
	v_lshlrev_b32_e32 v22, 16, v49
	v_mul_f32_e32 v0, 0xbfb8aa3b, v22
	v_exp_f32_e32 v0, v0
	v_and_b32_e32 v23, 0xffff0000, v49
	v_cvt_pk_bf16_f32 v20, v20, v21
	v_add_f32_e32 v0, 1.0, v0
	v_rcp_f32_e32 v48, v0
	v_mul_f32_e32 v0, 0xbfb8aa3b, v23
	v_exp_f32_e32 v0, v0
	s_nop 0
	v_add_f32_e32 v0, 1.0, v0
	v_rcp_f32_e32 v49, v0
	s_nop 0
	v_pk_mul_f32 v[22:23], v[48:49], v[22:23]
	s_nop 0
	v_pk_mul_f32 v[22:23], v[24:25], v[22:23]
	v_pk_mul_f32 v[24:25], v[26:27], v[34:35] op_sel_hi:[1,0]
	v_cvt_pk_bf16_f32 v21, v22, v23
	v_readfirstlane_b32 s98, v18
	v_readfirstlane_b32 s99, v19
	v_mov_b32_e32 v104, v20
	v_mov_b32_e32 v105, v21
	s_nop 1
	v_permlane32_swap_b32_e32 v104, v106
	v_permlane32_swap_b32_e32 v105, v107
	ds_write_b128 v118, v[104:107]
	s_waitcnt vmcnt(2)
	v_permlane32_swap_b32_e32 v190, v192
	v_permlane32_swap_b32_e32 v191, v193
	v_mov_b32_e32 v44, v190
	v_mov_b32_e32 v45, v191
	v_mov_b32_e32 v46, v192
	v_mov_b32_e32 v47, v193
	v_lshlrev_b32_e32 v20, 16, v46
	v_mul_f32_e32 v0, 0xbfb8aa3b, v20
	v_exp_f32_e32 v0, v0
	v_and_b32_e32 v21, 0xffff0000, v46
	v_pk_mul_f32 v[26:27], v[28:29], v[34:35] op_sel_hi:[1,0]
	v_add_f32_e32 v0, 1.0, v0
	v_rcp_f32_e32 v22, v0
	v_mul_f32_e32 v0, 0xbfb8aa3b, v21
	v_exp_f32_e32 v0, v0
	s_nop 0
	v_add_f32_e32 v0, 1.0, v0
	v_rcp_f32_e32 v23, v0
	s_nop 0
	v_pk_mul_f32 v[20:21], v[22:23], v[20:21]
	v_lshlrev_b32_e32 v22, 16, v47
	v_mul_f32_e32 v0, 0xbfb8aa3b, v22
	v_exp_f32_e32 v0, v0
	v_and_b32_e32 v23, 0xffff0000, v47
	v_pk_mul_f32 v[20:21], v[24:25], v[20:21]
	v_add_f32_e32 v0, 1.0, v0
	v_rcp_f32_e32 v24, v0
	v_mul_f32_e32 v0, 0xbfb8aa3b, v23
	v_exp_f32_e32 v0, v0
	v_cvt_pk_bf16_f32 v20, v20, v21
	v_add_f32_e32 v0, 1.0, v0
	v_rcp_f32_e32 v25, v0
	s_nop 0
	v_pk_mul_f32 v[22:23], v[24:25], v[22:23]
	s_nop 0
	v_pk_mul_f32 v[22:23], v[26:27], v[22:23]
	v_pk_mul_f32 v[24:25], v[30:31], v[34:35] op_sel_hi:[1,0]
	v_cvt_pk_bf16_f32 v21, v22, v23
	v_mov_b32_e32 v106, v20
	v_mov_b32_e32 v107, v21
	s_waitcnt vmcnt(2)
	v_lshlrev_b32_e32 v20, 16, v44
	v_mul_f32_e32 v0, 0xbfb8aa3b, v20
	v_exp_f32_e32 v0, v0
	v_and_b32_e32 v21, 0xffff0000, v44
	v_pk_mul_f32 v[26:27], v[32:33], v[34:35] op_sel_hi:[1,0]
	v_add_f32_e32 v0, 1.0, v0
	v_rcp_f32_e32 v22, v0
	v_mul_f32_e32 v0, 0xbfb8aa3b, v21
	v_exp_f32_e32 v0, v0
	s_nop 0
	v_add_f32_e32 v0, 1.0, v0
	v_rcp_f32_e32 v23, v0
	s_nop 0
	v_pk_mul_f32 v[20:21], v[22:23], v[20:21]
	v_lshlrev_b32_e32 v22, 16, v45
	v_mul_f32_e32 v0, 0xbfb8aa3b, v22
	v_exp_f32_e32 v0, v0
	v_and_b32_e32 v23, 0xffff0000, v45
	v_pk_mul_f32 v[20:21], v[24:25], v[20:21]
	v_add_f32_e32 v0, 1.0, v0
	v_rcp_f32_e32 v24, v0
	v_mul_f32_e32 v0, 0xbfb8aa3b, v23
	v_exp_f32_e32 v0, v0
	v_cvt_pk_bf16_f32 v20, v20, v21
	v_add_f32_e32 v0, 1.0, v0
	v_rcp_f32_e32 v25, v0
	s_nop 0
	v_pk_mul_f32 v[22:23], v[24:25], v[22:23]
	s_nop 0
	v_pk_mul_f32 v[22:23], v[26:27], v[22:23]
	s_nop 0
	v_cvt_pk_bf16_f32 v21, v22, v23
	v_mov_b32_e32 v104, v20
	v_mov_b32_e32 v105, v21
	s_nop 1
	v_permlane32_swap_b32_e32 v104, v106
	v_permlane32_swap_b32_e32 v105, v107
	ds_write_b128 v119, v[104:107]
	s_waitcnt vmcnt(1)
	v_permlane32_swap_b32_e32 v194, v196
	v_permlane32_swap_b32_e32 v195, v197
	v_mov_b32_e32 v40, v194
	v_mov_b32_e32 v41, v195
	v_mov_b32_e32 v42, v196
	v_mov_b32_e32 v43, v197
	v_lshlrev_b32_e32 v20, 16, v42
	v_mul_f32_e32 v0, 0xbfb8aa3b, v20
	v_exp_f32_e32 v0, v0
	v_and_b32_e32 v21, 0xffff0000, v42
	v_add_f32_e32 v0, 1.0, v0
	v_rcp_f32_e32 v22, v0
	v_mul_f32_e32 v0, 0xbfb8aa3b, v21
	v_exp_f32_e32 v0, v0
	s_nop 0
	v_add_f32_e32 v0, 1.0, v0
	v_rcp_f32_e32 v23, v0
	s_nop 0
	v_pk_mul_f32 v[20:21], v[22:23], v[20:21]
	s_nop 0
	v_pk_mul_f32 v[2:3], v[2:3], v[20:21]
	v_lshlrev_b32_e32 v20, 16, v43
	v_mul_f32_e32 v0, 0xbfb8aa3b, v20
	v_exp_f32_e32 v0, v0
	v_and_b32_e32 v21, 0xffff0000, v43
	v_cvt_pk_bf16_f32 v2, v2, v3
	v_add_f32_e32 v0, 1.0, v0
	v_rcp_f32_e32 v22, v0
	v_mul_f32_e32 v0, 0xbfb8aa3b, v21
	v_exp_f32_e32 v0, v0
	s_nop 0
	v_add_f32_e32 v0, 1.0, v0
	v_rcp_f32_e32 v23, v0
	s_nop 0
	v_pk_mul_f32 v[20:21], v[22:23], v[20:21]
	s_nop 0
	v_pk_mul_f32 v[4:5], v[4:5], v[20:21]
	s_nop 0
	v_cvt_pk_bf16_f32 v3, v4, v5
	v_mov_b32_e32 v106, v2
	v_mov_b32_e32 v107, v3
	s_waitcnt vmcnt(1)
	v_lshlrev_b32_e32 v2, 16, v40
	v_mul_f32_e32 v0, 0xbfb8aa3b, v2
	v_exp_f32_e32 v0, v0
	v_and_b32_e32 v3, 0xffff0000, v40
	v_add_f32_e32 v0, 1.0, v0
	v_rcp_f32_e32 v4, v0
	v_mul_f32_e32 v0, 0xbfb8aa3b, v3
	v_exp_f32_e32 v0, v0
	s_nop 0
	v_add_f32_e32 v0, 1.0, v0
	v_rcp_f32_e32 v5, v0
	s_nop 0
	v_pk_mul_f32 v[2:3], v[4:5], v[2:3]
	v_lshlrev_b32_e32 v4, 16, v41
	v_mul_f32_e32 v0, 0xbfb8aa3b, v4
	v_exp_f32_e32 v0, v0
	v_and_b32_e32 v5, 0xffff0000, v41
	v_pk_mul_f32 v[2:3], v[6:7], v[2:3]
	v_add_f32_e32 v0, 1.0, v0
	v_rcp_f32_e32 v6, v0
	v_mul_f32_e32 v0, 0xbfb8aa3b, v5
	v_exp_f32_e32 v0, v0
	v_cvt_pk_bf16_f32 v2, v2, v3
	v_add_f32_e32 v0, 1.0, v0
	v_rcp_f32_e32 v7, v0
	s_nop 0
	v_pk_mul_f32 v[4:5], v[6:7], v[4:5]
	s_nop 0
	v_pk_mul_f32 v[4:5], v[8:9], v[4:5]
	v_pk_mul_f32 v[6:7], v[10:11], v[34:35] op_sel_hi:[1,0]
	v_cvt_pk_bf16_f32 v3, v4, v5
	v_mov_b32_e32 v104, v2
	v_mov_b32_e32 v105, v3
	s_nop 1
	v_permlane32_swap_b32_e32 v104, v106
	v_permlane32_swap_b32_e32 v105, v107
	ds_write_b128 v120, v[104:107]
	s_waitcnt vmcnt(0)
	v_permlane32_swap_b32_e32 v198, v200
	v_permlane32_swap_b32_e32 v199, v201
	v_mov_b32_e32 v36, v198
	v_mov_b32_e32 v37, v199
	v_mov_b32_e32 v38, v200
	v_mov_b32_e32 v39, v201
	v_lshlrev_b32_e32 v2, 16, v38
	v_mul_f32_e32 v0, 0xbfb8aa3b, v2
	v_exp_f32_e32 v0, v0
	v_and_b32_e32 v3, 0xffff0000, v38
	v_pk_mul_f32 v[8:9], v[12:13], v[34:35] op_sel_hi:[1,0]
	v_add_f32_e32 v0, 1.0, v0
	v_rcp_f32_e32 v4, v0
	v_mul_f32_e32 v0, 0xbfb8aa3b, v3
	v_exp_f32_e32 v0, v0
	s_nop 0
	v_add_f32_e32 v0, 1.0, v0
	v_rcp_f32_e32 v5, v0
	s_nop 0
	v_pk_mul_f32 v[2:3], v[4:5], v[2:3]
	v_lshlrev_b32_e32 v4, 16, v39
	v_mul_f32_e32 v0, 0xbfb8aa3b, v4
	v_exp_f32_e32 v0, v0
	v_and_b32_e32 v5, 0xffff0000, v39
	v_pk_mul_f32 v[2:3], v[6:7], v[2:3]
	v_add_f32_e32 v0, 1.0, v0
	v_rcp_f32_e32 v6, v0
	v_mul_f32_e32 v0, 0xbfb8aa3b, v5
	v_exp_f32_e32 v0, v0
	v_cvt_pk_bf16_f32 v2, v2, v3
	v_add_f32_e32 v0, 1.0, v0
	v_rcp_f32_e32 v7, v0
	s_nop 0
	v_pk_mul_f32 v[4:5], v[6:7], v[4:5]
	s_nop 0
	v_pk_mul_f32 v[4:5], v[8:9], v[4:5]
	v_pk_mul_f32 v[6:7], v[14:15], v[34:35] op_sel_hi:[1,0]
	v_cvt_pk_bf16_f32 v3, v4, v5
	v_mov_b32_e32 v106, v2
	v_mov_b32_e32 v107, v3
	s_waitcnt vmcnt(0)
	v_lshlrev_b32_e32 v2, 16, v36
	v_mul_f32_e32 v0, 0xbfb8aa3b, v2
	v_exp_f32_e32 v0, v0
	v_and_b32_e32 v3, 0xffff0000, v36
	v_pk_mul_f32 v[8:9], v[16:17], v[34:35] op_sel_hi:[1,0]
	v_add_f32_e32 v0, 1.0, v0
	v_rcp_f32_e32 v4, v0
	v_mul_f32_e32 v0, 0xbfb8aa3b, v3
	v_exp_f32_e32 v0, v0
	s_nop 0
	v_add_f32_e32 v0, 1.0, v0
	v_rcp_f32_e32 v5, v0
	s_nop 0
	v_pk_mul_f32 v[2:3], v[4:5], v[2:3]
	v_lshlrev_b32_e32 v4, 16, v37
	v_mul_f32_e32 v0, 0xbfb8aa3b, v4
	v_exp_f32_e32 v0, v0
	v_and_b32_e32 v5, 0xffff0000, v37
	v_pk_mul_f32 v[2:3], v[6:7], v[2:3]
	v_add_f32_e32 v0, 1.0, v0
	v_rcp_f32_e32 v6, v0
	v_mul_f32_e32 v0, 0xbfb8aa3b, v5
	v_exp_f32_e32 v0, v0
	v_cvt_pk_bf16_f32 v2, v2, v3
	v_add_f32_e32 v0, 1.0, v0
	v_rcp_f32_e32 v7, v0
	s_nop 0
	v_pk_mul_f32 v[4:5], v[6:7], v[4:5]
	s_nop 0
	v_pk_mul_f32 v[4:5], v[8:9], v[4:5]
	s_nop 0
	v_cvt_pk_bf16_f32 v3, v4, v5
	v_mov_b32_e32 v104, v2
	v_mov_b32_e32 v105, v3
	s_nop 1
	v_permlane32_swap_b32_e32 v104, v106
	v_permlane32_swap_b32_e32 v105, v107
	ds_write_b128 v121, v[104:107]
	ds_read_b128 v[124:127], v122
	ds_read_b128 v[128:131], v122 offset:1024
	ds_read_b128 v[132:135], v122 offset:2048
	ds_read_b128 v[136:139], v122 offset:3072
	s_waitcnt lgkmcnt(3)
	global_store_dwordx4 v144, v[124:127], s[98:99] offset:1536 sc0 sc1
	s_waitcnt lgkmcnt(2)
	global_store_dwordx4 v145, v[128:131], s[98:99] offset:1536 sc0 sc1
	s_waitcnt lgkmcnt(1)
	global_store_dwordx4 v146, v[132:135], s[98:99] offset:1536 sc0 sc1
	s_waitcnt lgkmcnt(0)
	global_store_dwordx4 v147, v[136:139], s[98:99] offset:1536 sc0 sc1

.LBB0_175:
	s_waitcnt vmcnt(0) lgkmcnt(0)
	s_barrier
	v_mbcnt_lo_u32_b32 v116, -1, 0
	v_mbcnt_hi_u32_b32 v116, -1, v116
	v_mov_b32_e32 v148, s77
	v_lshlrev_b32_e32 v148, 6, v148
	v_and_b32_e32 v117, 31, v116
	v_lshrrev_b32_e32 v149, 5, v116
	v_lshl_add_u32 v122, v117, 7, v148
	v_and_b32_e32 v117, 7, v117
	v_sub_u32_e32 v118, 1, v149
	v_xor_b32_e32 v118, v118, v117
	v_lshl_add_u32 v118, v118, 4, v122
	v_sub_u32_e32 v119, 3, v149
	v_xor_b32_e32 v119, v119, v117
	v_lshl_add_u32 v119, v119, 4, v122
	v_sub_u32_e32 v120, 5, v149
	v_xor_b32_e32 v120, v120, v117
	v_lshl_add_u32 v120, v120, 4, v122
	v_sub_u32_e32 v121, 7, v149
	v_xor_b32_e32 v121, v121, v117
	v_lshl_add_u32 v121, v121, 4, v122
	v_lshrrev_b32_e32 v117, 3, v116
	v_and_b32_e32 v149, 7, v116
	v_lshl_add_u32 v122, v117, 7, v148
	v_xor_b32_e32 v148, v149, v117
	v_lshl_add_u32 v122, v148, 4, v122
	v_mul_u32_u24_e32 v144, 0x880, v117
	v_lshl_add_u32 v144, v149, 4, v144
	v_add_u32_e32 v145, 0x4400, v144
	v_add_u32_e32 v146, 0x8800, v144
	v_add_u32_e32 v147, 0xcc00, v144
	v_mbcnt_lo_u32_b32 v108, -1, 0
	v_mbcnt_hi_u32_b32 v108, -1, v108
	v_cmp_gt_u32_e32 vcc, 32, v108
	s_nop 1
	v_cndmask_b32_e64 v109, -1, 0, vcc
	v_cndmask_b32_e64 v108, -8, 16, vcc
	v_mbcnt_lo_u32_b32 v72, -1, 0
	v_mbcnt_hi_u32_b32 v72, -1, v72
	s_movk_i32 s0, 0x100
	v_add_u32_e32 v0, s77, v72
	v_cmp_gt_u32_e32 vcc, s0, v0
	v_mov_b32_e32 v66, s20
	v_mov_b32_e32 v67, s9
	v_cndmask_b32_e32 v70, v66, v67, vcc
	v_mov_b32_e32 v66, s43
	v_mov_b32_e32 v67, s21
	v_cndmask_b32_e32 v66, v66, v67, vcc
	v_and_b32_e32 v0, 0xc0, v0
	v_lshl_or_b32 v0, v66, 8, v0
	v_add_u32_e32 v0, s45, v0
	v_and_or_b32 v75, v72, 31, v0
	v_mov_b32_e32 v0, v151
	s_nop 1
	v_permlane32_swap_b32_e32 v151, v0
	v_mov_b64_e32 v[66:67], s[74:75]
	v_add_f32_e32 v74, v151, v0
	v_mad_u64_u32 v[68:69], s[0:1], v75, s4, v[66:67]
	v_lshlrev_b32_e32 v0, 7, v70
	v_lshrrev_b32_e32 v66, 2, v72
	v_lshl_add_u64 v[70:71], v[68:69], 0, v[0:1]
	v_and_b32_e32 v66, 8, v66
	v_mov_b32_e32 v67, v1
	v_lshl_add_u64 v[70:71], v[70:71], 0, v[66:67]
	s_mov_b64 s[22:23], 0x4400d00
	s_mov_b32 s5, 0x4400000
	v_lshl_add_u64 v[86:87], v[70:71], 0, s[22:23]
	v_add_co_u32_e32 v70, vcc, s5, v70
	v_rcp_f32_e32 v74, v74
	s_nop 0
	v_addc_co_u32_e32 v71, vcc, 0, v71, vcc
	v_lshl_add_u64 v[114:115], v[86:87], 0, v[108:109]
	global_load_dwordx4 v[170:173], v[114:115], off nt
	global_load_dwordx4 v[174:177], v[114:115], off offset:32 nt
	global_load_dwordx4 v[178:181], v[114:115], off offset:64 nt
	global_load_dwordx4 v[182:185], v[114:115], off offset:96 nt
	v_pk_mul_f32 v[50:51], v[50:51], v[74:75] op_sel_hi:[1,0]
	s_movk_i32 s18, 0xf3c0
	v_mad_u64_u32 v[84:85], s[0:1], v75, s18, v[68:69]
	v_pk_mul_f32 v[52:53], v[52:53], v[74:75] op_sel_hi:[1,0]
	v_sub_u32_e32 v85, v85, v75
	v_lshl_add_u64 v[84:85], v[84:85], 0, v[0:1]
	v_pk_mul_f32 v[54:55], v[54:55], v[74:75] op_sel_hi:[1,0]
	v_pk_mul_f32 v[56:57], v[56:57], v[74:75] op_sel_hi:[1,0]
	v_pk_mul_f32 v[34:35], v[34:35], v[74:75] op_sel_hi:[1,0]
	v_pk_mul_f32 v[36:37], v[36:37], v[74:75] op_sel_hi:[1,0]
	v_pk_mul_f32 v[38:39], v[38:39], v[74:75] op_sel_hi:[1,0]
	v_pk_mul_f32 v[40:41], v[40:41], v[74:75] op_sel_hi:[1,0]
	s_mov_b64 s[0:1], 0x29800
	s_waitcnt vmcnt(3)
	v_permlane32_swap_b32_e32 v170, v172
	v_permlane32_swap_b32_e32 v171, v173
	v_mov_b32_e32 v90, v170
	v_mov_b32_e32 v91, v171
	v_mov_b32_e32 v88, v172
	v_mov_b32_e32 v89, v173
	v_lshlrev_b32_e32 v86, 16, v88
	v_and_b32_e32 v87, 0xffff0000, v88
	v_mul_f32_e32 v88, 0xbfb8aa3b, v86
	v_exp_f32_e32 v88, v88
	s_nop 0
	v_add_f32_e32 v88, 1.0, v88
	v_rcp_f32_e32 v92, v88
	v_mul_f32_e32 v88, 0xbfb8aa3b, v87
	v_exp_f32_e32 v88, v88
	s_nop 0
	v_add_f32_e32 v88, 1.0, v88
	v_rcp_f32_e32 v93, v88
	s_nop 0
	v_pk_mul_f32 v[86:87], v[92:93], v[86:87]
	s_nop 0
	v_pk_mul_f32 v[50:51], v[50:51], v[86:87]
	v_lshlrev_b32_e32 v86, 16, v89
	v_and_b32_e32 v87, 0xffff0000, v89
	v_mul_f32_e32 v88, 0xbfb8aa3b, v86
	v_mul_f32_e32 v89, 0xbfb8aa3b, v87
	v_exp_f32_e32 v88, v88
	v_exp_f32_e32 v89, v89
	v_add_f32_e32 v88, 1.0, v88
	v_add_f32_e32 v89, 1.0, v89
	v_rcp_f32_e32 v88, v88
	v_rcp_f32_e32 v89, v89
	s_nop 0
	v_pk_mul_f32 v[86:87], v[88:89], v[86:87]
	s_nop 0
	v_pk_mul_f32 v[52:53], v[52:53], v[86:87]
	v_cvt_pk_bf16_f32 v86, v50, v51
	v_cvt_pk_bf16_f32 v87, v52, v53
	s_waitcnt vmcnt(3)
	v_lshlrev_b32_e32 v52, 16, v90
	v_and_b32_e32 v53, 0xffff0000, v90
	v_lshl_add_u64 v[50:51], v[84:85], 0, v[66:67]
	v_mul_f32_e32 v84, 0xbfb8aa3b, v52
	v_mul_f32_e32 v85, 0xbfb8aa3b, v53
	v_exp_f32_e32 v84, v84
	v_exp_f32_e32 v85, v85
	v_mov_b32_e32 v106, v86
	v_mov_b32_e32 v107, v87
	v_add_f32_e32 v84, 1.0, v84
	v_add_f32_e32 v85, 1.0, v85
	v_rcp_f32_e32 v84, v84
	v_rcp_f32_e32 v85, v85
	s_nop 0
	v_pk_mul_f32 v[52:53], v[84:85], v[52:53]
	s_nop 0
	v_pk_mul_f32 v[52:53], v[54:55], v[52:53]
	v_lshlrev_b32_e32 v54, 16, v91
	v_and_b32_e32 v55, 0xffff0000, v91
	v_mul_f32_e32 v84, 0xbfb8aa3b, v54
	v_mul_f32_e32 v85, 0xbfb8aa3b, v55
	v_exp_f32_e32 v84, v84
	v_exp_f32_e32 v85, v85
	v_cvt_pk_bf16_f32 v52, v52, v53
	v_add_f32_e32 v84, 1.0, v84
	v_add_f32_e32 v85, 1.0, v85
	v_rcp_f32_e32 v84, v84
	v_rcp_f32_e32 v85, v85
	s_nop 0
	v_pk_mul_f32 v[54:55], v[84:85], v[54:55]
	s_nop 0
	v_pk_mul_f32 v[54:55], v[56:57], v[54:55]
	v_pk_mul_f32 v[56:57], v[58:59], v[74:75] op_sel_hi:[1,0]
	v_cvt_pk_bf16_f32 v53, v54, v55
	v_readfirstlane_b32 s98, v50
	v_readfirstlane_b32 s99, v51
	v_mov_b32_e32 v104, v52
	v_mov_b32_e32 v105, v53
	s_nop 1
	v_permlane32_swap_b32_e32 v104, v106
	v_permlane32_swap_b32_e32 v105, v107
	ds_write_b128 v118, v[104:107]
	s_waitcnt vmcnt(2)
	v_permlane32_swap_b32_e32 v174, v176
	v_permlane32_swap_b32_e32 v175, v177
	v_mov_b32_e32 v80, v174
	v_mov_b32_e32 v81, v175
	v_mov_b32_e32 v82, v176
	v_mov_b32_e32 v83, v177
	v_lshlrev_b32_e32 v52, 16, v82
	v_and_b32_e32 v53, 0xffff0000, v82
	v_mul_f32_e32 v54, 0xbfb8aa3b, v52
	v_mul_f32_e32 v55, 0xbfb8aa3b, v53
	v_exp_f32_e32 v54, v54
	v_exp_f32_e32 v55, v55
	v_pk_mul_f32 v[58:59], v[60:61], v[74:75] op_sel_hi:[1,0]
	v_add_f32_e32 v54, 1.0, v54
	v_add_f32_e32 v55, 1.0, v55
	v_rcp_f32_e32 v54, v54
	v_rcp_f32_e32 v55, v55
	s_nop 0
	v_pk_mul_f32 v[52:53], v[54:55], v[52:53]
	v_lshlrev_b32_e32 v54, 16, v83
	v_and_b32_e32 v55, 0xffff0000, v83
	v_pk_mul_f32 v[52:53], v[56:57], v[52:53]
	v_mul_f32_e32 v56, 0xbfb8aa3b, v54
	v_mul_f32_e32 v57, 0xbfb8aa3b, v55
	v_exp_f32_e32 v56, v56
	v_exp_f32_e32 v57, v57
	v_cvt_pk_bf16_f32 v52, v52, v53
	v_add_f32_e32 v56, 1.0, v56
	v_add_f32_e32 v57, 1.0, v57
	v_rcp_f32_e32 v56, v56
	v_rcp_f32_e32 v57, v57
	s_nop 0
	v_pk_mul_f32 v[54:55], v[56:57], v[54:55]
	s_nop 0
	v_pk_mul_f32 v[54:55], v[58:59], v[54:55]
	v_pk_mul_f32 v[56:57], v[62:63], v[74:75] op_sel_hi:[1,0]
	v_cvt_pk_bf16_f32 v53, v54, v55
	v_mov_b32_e32 v106, v52
	v_mov_b32_e32 v107, v53
	s_waitcnt vmcnt(2)
	v_lshlrev_b32_e32 v52, 16, v80
	v_and_b32_e32 v53, 0xffff0000, v80
	v_mul_f32_e32 v54, 0xbfb8aa3b, v52
	v_mul_f32_e32 v55, 0xbfb8aa3b, v53
	v_exp_f32_e32 v54, v54
	v_exp_f32_e32 v55, v55
	v_pk_mul_f32 v[58:59], v[64:65], v[74:75] op_sel_hi:[1,0]
	v_add_f32_e32 v54, 1.0, v54
	v_add_f32_e32 v55, 1.0, v55
	v_rcp_f32_e32 v54, v54
	v_rcp_f32_e32 v55, v55
	s_nop 0
	v_pk_mul_f32 v[52:53], v[54:55], v[52:53]
	v_lshlrev_b32_e32 v54, 16, v81
	v_and_b32_e32 v55, 0xffff0000, v81
	v_pk_mul_f32 v[52:53], v[56:57], v[52:53]
	v_mul_f32_e32 v56, 0xbfb8aa3b, v54
	v_mul_f32_e32 v57, 0xbfb8aa3b, v55
	v_exp_f32_e32 v56, v56
	v_exp_f32_e32 v57, v57
	v_cvt_pk_bf16_f32 v52, v52, v53
	v_add_f32_e32 v56, 1.0, v56
	v_add_f32_e32 v57, 1.0, v57
	v_rcp_f32_e32 v56, v56
	v_rcp_f32_e32 v57, v57
	s_nop 0
	v_pk_mul_f32 v[54:55], v[56:57], v[54:55]
	s_nop 0
	v_pk_mul_f32 v[54:55], v[58:59], v[54:55]
	s_nop 0
	v_cvt_pk_bf16_f32 v53, v54, v55
	v_mov_b32_e32 v104, v52
	v_mov_b32_e32 v105, v53
	s_nop 1
	v_permlane32_swap_b32_e32 v104, v106
	v_permlane32_swap_b32_e32 v105, v107
	ds_write_b128 v119, v[104:107]
	s_waitcnt vmcnt(1)
	v_permlane32_swap_b32_e32 v178, v180
	v_permlane32_swap_b32_e32 v179, v181
	v_mov_b32_e32 v76, v178
	v_mov_b32_e32 v77, v179
	v_mov_b32_e32 v78, v180
	v_mov_b32_e32 v79, v181
	v_lshlrev_b32_e32 v52, 16, v78
	v_and_b32_e32 v53, 0xffff0000, v78
	v_mul_f32_e32 v54, 0xbfb8aa3b, v52
	v_mul_f32_e32 v55, 0xbfb8aa3b, v53
	v_exp_f32_e32 v54, v54
	v_exp_f32_e32 v55, v55
	v_add_f32_e32 v54, 1.0, v54
	v_add_f32_e32 v55, 1.0, v55
	v_rcp_f32_e32 v54, v54
	v_rcp_f32_e32 v55, v55
	s_nop 0
	v_pk_mul_f32 v[52:53], v[54:55], v[52:53]
	s_nop 0
	v_pk_mul_f32 v[34:35], v[34:35], v[52:53]
	v_lshlrev_b32_e32 v52, 16, v79
	v_and_b32_e32 v53, 0xffff0000, v79
	v_mul_f32_e32 v54, 0xbfb8aa3b, v52
	v_mul_f32_e32 v55, 0xbfb8aa3b, v53
	v_exp_f32_e32 v54, v54
	v_exp_f32_e32 v55, v55
	v_cvt_pk_bf16_f32 v34, v34, v35
	v_add_f32_e32 v54, 1.0, v54
	v_add_f32_e32 v55, 1.0, v55
	v_rcp_f32_e32 v54, v54
	v_rcp_f32_e32 v55, v55
	s_nop 0
	v_pk_mul_f32 v[52:53], v[54:55], v[52:53]
	s_nop 0
	v_pk_mul_f32 v[36:37], v[36:37], v[52:53]
	s_nop 0
	v_cvt_pk_bf16_f32 v35, v36, v37
	v_mov_b32_e32 v106, v34
	v_mov_b32_e32 v107, v35
	s_waitcnt vmcnt(1)
	v_lshlrev_b32_e32 v34, 16, v76
	v_and_b32_e32 v35, 0xffff0000, v76
	v_mul_f32_e32 v36, 0xbfb8aa3b, v34
	v_mul_f32_e32 v37, 0xbfb8aa3b, v35
	v_exp_f32_e32 v36, v36
	v_exp_f32_e32 v37, v37
	v_add_f32_e32 v36, 1.0, v36
	v_add_f32_e32 v37, 1.0, v37
	v_rcp_f32_e32 v36, v36
	v_rcp_f32_e32 v37, v37
	s_nop 0
	v_pk_mul_f32 v[34:35], v[36:37], v[34:35]
	v_lshlrev_b32_e32 v36, 16, v77
	v_and_b32_e32 v37, 0xffff0000, v77
	v_pk_mul_f32 v[34:35], v[38:39], v[34:35]
	v_mul_f32_e32 v38, 0xbfb8aa3b, v36
	v_mul_f32_e32 v39, 0xbfb8aa3b, v37
	v_exp_f32_e32 v38, v38
	v_exp_f32_e32 v39, v39
	v_cvt_pk_bf16_f32 v34, v34, v35
	v_add_f32_e32 v38, 1.0, v38
	v_add_f32_e32 v39, 1.0, v39
	v_rcp_f32_e32 v38, v38
	v_rcp_f32_e32 v39, v39
	s_nop 0
	v_pk_mul_f32 v[36:37], v[38:39], v[36:37]
	s_nop 0
	v_pk_mul_f32 v[36:37], v[40:41], v[36:37]
	v_pk_mul_f32 v[38:39], v[42:43], v[74:75] op_sel_hi:[1,0]
	v_cvt_pk_bf16_f32 v35, v36, v37
	v_mov_b32_e32 v104, v34
	v_mov_b32_e32 v105, v35
	s_nop 1
	v_permlane32_swap_b32_e32 v104, v106
	v_permlane32_swap_b32_e32 v105, v107
	ds_write_b128 v120, v[104:107]
	s_waitcnt vmcnt(0)
	v_permlane32_swap_b32_e32 v182, v184
	v_permlane32_swap_b32_e32 v183, v185
	v_mov_b32_e32 v70, v182
	v_mov_b32_e32 v71, v183
	v_mov_b32_e32 v72, v184
	v_mov_b32_e32 v73, v185
	v_lshlrev_b32_e32 v34, 16, v72
	v_and_b32_e32 v35, 0xffff0000, v72
	v_mul_f32_e32 v36, 0xbfb8aa3b, v34
	v_mul_f32_e32 v37, 0xbfb8aa3b, v35
	v_exp_f32_e32 v36, v36
	v_exp_f32_e32 v37, v37
	v_pk_mul_f32 v[40:41], v[44:45], v[74:75] op_sel_hi:[1,0]
	v_add_f32_e32 v36, 1.0, v36
	v_add_f32_e32 v37, 1.0, v37
	v_rcp_f32_e32 v36, v36
	v_rcp_f32_e32 v37, v37
	s_nop 0
	v_pk_mul_f32 v[34:35], v[36:37], v[34:35]
	v_lshlrev_b32_e32 v36, 16, v73
	v_and_b32_e32 v37, 0xffff0000, v73
	v_pk_mul_f32 v[34:35], v[38:39], v[34:35]
	v_mul_f32_e32 v38, 0xbfb8aa3b, v36
	v_mul_f32_e32 v39, 0xbfb8aa3b, v37
	v_exp_f32_e32 v38, v38
	v_exp_f32_e32 v39, v39
	v_cvt_pk_bf16_f32 v34, v34, v35
	v_add_f32_e32 v38, 1.0, v38
	v_add_f32_e32 v39, 1.0, v39
	v_rcp_f32_e32 v38, v38
	v_rcp_f32_e32 v39, v39
	s_nop 0
	v_pk_mul_f32 v[36:37], v[38:39], v[36:37]
	s_nop 0
	v_pk_mul_f32 v[36:37], v[40:41], v[36:37]
	v_pk_mul_f32 v[38:39], v[46:47], v[74:75] op_sel_hi:[1,0]
	v_cvt_pk_bf16_f32 v35, v36, v37
	v_mov_b32_e32 v106, v34
	v_mov_b32_e32 v107, v35
	s_waitcnt vmcnt(0)
	v_lshlrev_b32_e32 v34, 16, v70
	v_and_b32_e32 v35, 0xffff0000, v70
	v_mul_f32_e32 v36, 0xbfb8aa3b, v34
	v_mul_f32_e32 v37, 0xbfb8aa3b, v35
	v_exp_f32_e32 v36, v36
	v_exp_f32_e32 v37, v37
	v_pk_mul_f32 v[40:41], v[48:49], v[74:75] op_sel_hi:[1,0]
	v_add_f32_e32 v36, 1.0, v36
	v_add_f32_e32 v37, 1.0, v37
	v_rcp_f32_e32 v36, v36
	v_rcp_f32_e32 v37, v37
	s_nop 0
	v_pk_mul_f32 v[34:35], v[36:37], v[34:35]
	v_lshlrev_b32_e32 v36, 16, v71
	v_and_b32_e32 v37, 0xffff0000, v71
	v_pk_mul_f32 v[34:35], v[38:39], v[34:35]
	v_mul_f32_e32 v38, 0xbfb8aa3b, v36
	v_mul_f32_e32 v39, 0xbfb8aa3b, v37
	v_exp_f32_e32 v38, v38
	v_exp_f32_e32 v39, v39
	v_cvt_pk_bf16_f32 v34, v34, v35
	v_add_f32_e32 v38, 1.0, v38
	v_add_f32_e32 v39, 1.0, v39
	v_rcp_f32_e32 v38, v38
	v_rcp_f32_e32 v39, v39
	s_nop 0
	v_pk_mul_f32 v[36:37], v[38:39], v[36:37]
	s_nop 0
	v_pk_mul_f32 v[36:37], v[40:41], v[36:37]
	v_or_b32_e32 v38, 32, v75
	v_cvt_pk_bf16_f32 v35, v36, v37
	v_mov_b32_e32 v104, v34
	v_mov_b32_e32 v105, v35
	s_nop 1
	v_permlane32_swap_b32_e32 v104, v106
	v_permlane32_swap_b32_e32 v105, v107
	ds_write_b128 v121, v[104:107]
	ds_read_b128 v[124:127], v122
	ds_read_b128 v[128:131], v122 offset:1024
	ds_read_b128 v[132:135], v122 offset:2048
	ds_read_b128 v[136:139], v122 offset:3072
	s_waitcnt lgkmcnt(3)
	global_store_dwordx4 v144, v[124:127], s[98:99] offset:768 sc0 sc1
	s_waitcnt lgkmcnt(2)
	global_store_dwordx4 v145, v[128:131], s[98:99] offset:768 sc0 sc1
	s_waitcnt lgkmcnt(1)
	global_store_dwordx4 v146, v[132:135], s[98:99] offset:768 sc0 sc1
	s_waitcnt lgkmcnt(0)
	global_store_dwordx4 v147, v[136:139], s[98:99] offset:768 sc0 sc1
	v_mov_b32_e32 v34, v150
	s_nop 1
	v_permlane32_swap_b32_e32 v150, v34
	v_add_f32_e32 v54, v150, v34
	v_lshl_add_u64 v[34:35], v[68:69], 0, s[0:1]
	v_lshl_add_u64 v[36:37], v[34:35], 0, v[0:1]
	v_lshl_add_u64 v[36:37], v[36:37], 0, v[66:67]
	v_mad_u64_u32 v[52:53], s[0:1], v38, s18, v[34:35]
	v_lshl_add_u64 v[34:35], v[36:37], 0, s[22:23]
	v_add_co_u32_e32 v36, vcc, s5, v36
	v_sub_u32_e32 v53, v53, v38
	s_nop 0
	v_addc_co_u32_e32 v37, vcc, 0, v37, vcc
	v_lshl_add_u64 v[116:117], v[34:35], 0, v[108:109]
	global_load_dwordx4 v[186:189], v[116:117], off nt
	global_load_dwordx4 v[190:193], v[116:117], off offset:32 nt
	global_load_dwordx4 v[194:197], v[116:117], off offset:64 nt
	global_load_dwordx4 v[198:201], v[116:117], off offset:96 nt
	v_rcp_f32_e32 v34, v54
	v_lshl_add_u64 v[52:53], v[52:53], 0, v[0:1]
	s_mov_b64 s[0:1], 0
	v_pk_mul_f32 v[18:19], v[18:19], v[34:35] op_sel_hi:[1,0]
	v_pk_mul_f32 v[20:21], v[20:21], v[34:35] op_sel_hi:[1,0]
	v_pk_mul_f32 v[22:23], v[22:23], v[34:35] op_sel_hi:[1,0]
	v_pk_mul_f32 v[24:25], v[24:25], v[34:35] op_sel_hi:[1,0]
	v_pk_mul_f32 v[2:3], v[2:3], v[34:35] op_sel_hi:[1,0]
	v_pk_mul_f32 v[4:5], v[4:5], v[34:35] op_sel_hi:[1,0]
	v_pk_mul_f32 v[6:7], v[6:7], v[34:35] op_sel_hi:[1,0]
	v_pk_mul_f32 v[8:9], v[8:9], v[34:35] op_sel_hi:[1,0]
	s_waitcnt vmcnt(3)
	v_permlane32_swap_b32_e32 v186, v188
	v_permlane32_swap_b32_e32 v187, v189
	v_mov_b32_e32 v48, v186
	v_mov_b32_e32 v49, v187
	v_mov_b32_e32 v50, v188
	v_mov_b32_e32 v51, v189
	v_lshlrev_b32_e32 v54, 16, v50
	v_mul_f32_e32 v0, 0xbfb8aa3b, v54
	v_exp_f32_e32 v0, v0
	v_and_b32_e32 v55, 0xffff0000, v50
	v_lshlrev_b32_e32 v50, 16, v51
	v_and_b32_e32 v51, 0xffff0000, v51
	v_add_f32_e32 v0, 1.0, v0
	v_rcp_f32_e32 v56, v0
	v_mul_f32_e32 v0, 0xbfb8aa3b, v55
	v_exp_f32_e32 v0, v0
	s_nop 0
	v_add_f32_e32 v0, 1.0, v0
	v_rcp_f32_e32 v57, v0
	v_mul_f32_e32 v0, 0xbfb8aa3b, v50
	v_exp_f32_e32 v0, v0
	v_pk_mul_f32 v[54:55], v[56:57], v[54:55]
	s_nop 0
	v_pk_mul_f32 v[18:19], v[18:19], v[54:55]
	v_add_f32_e32 v0, 1.0, v0
	v_rcp_f32_e32 v54, v0
	v_mul_f32_e32 v0, 0xbfb8aa3b, v51
	v_exp_f32_e32 v0, v0
	s_nop 0
	v_add_f32_e32 v0, 1.0, v0
	v_rcp_f32_e32 v55, v0
	s_nop 0
	v_pk_mul_f32 v[50:51], v[54:55], v[50:51]
	s_nop 0
	v_pk_mul_f32 v[20:21], v[20:21], v[50:51]
	v_cvt_pk_bf16_f32 v50, v18, v19
	v_cvt_pk_bf16_f32 v51, v20, v21
	s_waitcnt vmcnt(3)
	v_lshlrev_b32_e32 v20, 16, v48
	v_mul_f32_e32 v0, 0xbfb8aa3b, v20
	v_exp_f32_e32 v0, v0
	v_lshl_add_u64 v[18:19], v[52:53], 0, v[66:67]
	v_and_b32_e32 v21, 0xffff0000, v48
	v_mov_b32_e32 v106, v50
	v_mov_b32_e32 v107, v51
	v_add_f32_e32 v0, 1.0, v0
	v_rcp_f32_e32 v50, v0
	v_mul_f32_e32 v0, 0xbfb8aa3b, v21
	v_exp_f32_e32 v0, v0
	s_nop 0
	v_add_f32_e32 v0, 1.0, v0
	v_rcp_f32_e32 v51, v0
	s_nop 0
	v_pk_mul_f32 v[20:21], v[50:51], v[20:21]
	s_nop 0
	v_pk_mul_f32 v[20:21], v[22:23], v[20:21]
	v_lshlrev_b32_e32 v22, 16, v49
	v_mul_f32_e32 v0, 0xbfb8aa3b, v22
	v_exp_f32_e32 v0, v0
	v_and_b32_e32 v23, 0xffff0000, v49
	v_cvt_pk_bf16_f32 v20, v20, v21
	v_add_f32_e32 v0, 1.0, v0
	v_rcp_f32_e32 v48, v0
	v_mul_f32_e32 v0, 0xbfb8aa3b, v23
	v_exp_f32_e32 v0, v0
	s_nop 0
	v_add_f32_e32 v0, 1.0, v0
	v_rcp_f32_e32 v49, v0
	s_nop 0
	v_pk_mul_f32 v[22:23], v[48:49], v[22:23]
	s_nop 0
	v_pk_mul_f32 v[22:23], v[24:25], v[22:23]
	v_pk_mul_f32 v[24:25], v[26:27], v[34:35] op_sel_hi:[1,0]
	v_cvt_pk_bf16_f32 v21, v22, v23
	v_readfirstlane_b32 s98, v18
	v_readfirstlane_b32 s99, v19
	v_mov_b32_e32 v104, v20
	v_mov_b32_e32 v105, v21
	s_nop 1
	v_permlane32_swap_b32_e32 v104, v106
	v_permlane32_swap_b32_e32 v105, v107
	ds_write_b128 v118, v[104:107]
	s_waitcnt vmcnt(2)
	v_permlane32_swap_b32_e32 v190, v192
	v_permlane32_swap_b32_e32 v191, v193
	v_mov_b32_e32 v44, v190
	v_mov_b32_e32 v45, v191
	v_mov_b32_e32 v46, v192
	v_mov_b32_e32 v47, v193
	v_lshlrev_b32_e32 v20, 16, v46
	v_mul_f32_e32 v0, 0xbfb8aa3b, v20
	v_exp_f32_e32 v0, v0
	v_and_b32_e32 v21, 0xffff0000, v46
	v_pk_mul_f32 v[26:27], v[28:29], v[34:35] op_sel_hi:[1,0]
	v_add_f32_e32 v0, 1.0, v0
	v_rcp_f32_e32 v22, v0
	v_mul_f32_e32 v0, 0xbfb8aa3b, v21
	v_exp_f32_e32 v0, v0
	s_nop 0
	v_add_f32_e32 v0, 1.0, v0
	v_rcp_f32_e32 v23, v0
	s_nop 0
	v_pk_mul_f32 v[20:21], v[22:23], v[20:21]
	v_lshlrev_b32_e32 v22, 16, v47
	v_mul_f32_e32 v0, 0xbfb8aa3b, v22
	v_exp_f32_e32 v0, v0
	v_and_b32_e32 v23, 0xffff0000, v47
	v_pk_mul_f32 v[20:21], v[24:25], v[20:21]
	v_add_f32_e32 v0, 1.0, v0
	v_rcp_f32_e32 v24, v0
	v_mul_f32_e32 v0, 0xbfb8aa3b, v23
	v_exp_f32_e32 v0, v0
	v_cvt_pk_bf16_f32 v20, v20, v21
	v_add_f32_e32 v0, 1.0, v0
	v_rcp_f32_e32 v25, v0
	s_nop 0
	v_pk_mul_f32 v[22:23], v[24:25], v[22:23]
	s_nop 0
	v_pk_mul_f32 v[22:23], v[26:27], v[22:23]
	v_pk_mul_f32 v[24:25], v[30:31], v[34:35] op_sel_hi:[1,0]
	v_cvt_pk_bf16_f32 v21, v22, v23
	v_mov_b32_e32 v106, v20
	v_mov_b32_e32 v107, v21
	s_waitcnt vmcnt(2)
	v_lshlrev_b32_e32 v20, 16, v44
	v_mul_f32_e32 v0, 0xbfb8aa3b, v20
	v_exp_f32_e32 v0, v0
	v_and_b32_e32 v21, 0xffff0000, v44
	v_pk_mul_f32 v[26:27], v[32:33], v[34:35] op_sel_hi:[1,0]
	v_add_f32_e32 v0, 1.0, v0
	v_rcp_f32_e32 v22, v0
	v_mul_f32_e32 v0, 0xbfb8aa3b, v21
	v_exp_f32_e32 v0, v0
	s_nop 0
	v_add_f32_e32 v0, 1.0, v0
	v_rcp_f32_e32 v23, v0
	s_nop 0
	v_pk_mul_f32 v[20:21], v[22:23], v[20:21]
	v_lshlrev_b32_e32 v22, 16, v45
	v_mul_f32_e32 v0, 0xbfb8aa3b, v22
	v_exp_f32_e32 v0, v0
	v_and_b32_e32 v23, 0xffff0000, v45
	v_pk_mul_f32 v[20:21], v[24:25], v[20:21]
	v_add_f32_e32 v0, 1.0, v0
	v_rcp_f32_e32 v24, v0
	v_mul_f32_e32 v0, 0xbfb8aa3b, v23
	v_exp_f32_e32 v0, v0
	v_cvt_pk_bf16_f32 v20, v20, v21
	v_add_f32_e32 v0, 1.0, v0
	v_rcp_f32_e32 v25, v0
	s_nop 0
	v_pk_mul_f32 v[22:23], v[24:25], v[22:23]
	s_nop 0
	v_pk_mul_f32 v[22:23], v[26:27], v[22:23]
	s_nop 0
	v_cvt_pk_bf16_f32 v21, v22, v23
	v_mov_b32_e32 v104, v20
	v_mov_b32_e32 v105, v21
	s_nop 1
	v_permlane32_swap_b32_e32 v104, v106
	v_permlane32_swap_b32_e32 v105, v107
	ds_write_b128 v119, v[104:107]
	s_waitcnt vmcnt(1)
	v_permlane32_swap_b32_e32 v194, v196
	v_permlane32_swap_b32_e32 v195, v197
	v_mov_b32_e32 v40, v194
	v_mov_b32_e32 v41, v195
	v_mov_b32_e32 v42, v196
	v_mov_b32_e32 v43, v197
	v_lshlrev_b32_e32 v20, 16, v42
	v_mul_f32_e32 v0, 0xbfb8aa3b, v20
	v_exp_f32_e32 v0, v0
	v_and_b32_e32 v21, 0xffff0000, v42
	v_add_f32_e32 v0, 1.0, v0
	v_rcp_f32_e32 v22, v0
	v_mul_f32_e32 v0, 0xbfb8aa3b, v21
	v_exp_f32_e32 v0, v0
	s_nop 0
	v_add_f32_e32 v0, 1.0, v0
	v_rcp_f32_e32 v23, v0
	s_nop 0
	v_pk_mul_f32 v[20:21], v[22:23], v[20:21]
	s_nop 0
	v_pk_mul_f32 v[2:3], v[2:3], v[20:21]
	v_lshlrev_b32_e32 v20, 16, v43
	v_mul_f32_e32 v0, 0xbfb8aa3b, v20
	v_exp_f32_e32 v0, v0
	v_and_b32_e32 v21, 0xffff0000, v43
	v_cvt_pk_bf16_f32 v2, v2, v3
	v_add_f32_e32 v0, 1.0, v0
	v_rcp_f32_e32 v22, v0
	v_mul_f32_e32 v0, 0xbfb8aa3b, v21
	v_exp_f32_e32 v0, v0
	s_nop 0
	v_add_f32_e32 v0, 1.0, v0
	v_rcp_f32_e32 v23, v0
	s_nop 0
	v_pk_mul_f32 v[20:21], v[22:23], v[20:21]
	s_nop 0
	v_pk_mul_f32 v[4:5], v[4:5], v[20:21]
	s_nop 0
	v_cvt_pk_bf16_f32 v3, v4, v5
	v_mov_b32_e32 v106, v2
	v_mov_b32_e32 v107, v3
	s_waitcnt vmcnt(1)
	v_lshlrev_b32_e32 v2, 16, v40
	v_mul_f32_e32 v0, 0xbfb8aa3b, v2
	v_exp_f32_e32 v0, v0
	v_and_b32_e32 v3, 0xffff0000, v40
	v_add_f32_e32 v0, 1.0, v0
	v_rcp_f32_e32 v4, v0
	v_mul_f32_e32 v0, 0xbfb8aa3b, v3
	v_exp_f32_e32 v0, v0
	s_nop 0
	v_add_f32_e32 v0, 1.0, v0
	v_rcp_f32_e32 v5, v0
	s_nop 0
	v_pk_mul_f32 v[2:3], v[4:5], v[2:3]
	v_lshlrev_b32_e32 v4, 16, v41
	v_mul_f32_e32 v0, 0xbfb8aa3b, v4
	v_exp_f32_e32 v0, v0
	v_and_b32_e32 v5, 0xffff0000, v41
	v_pk_mul_f32 v[2:3], v[6:7], v[2:3]
	v_add_f32_e32 v0, 1.0, v0
	v_rcp_f32_e32 v6, v0
	v_mul_f32_e32 v0, 0xbfb8aa3b, v5
	v_exp_f32_e32 v0, v0
	v_cvt_pk_bf16_f32 v2, v2, v3
	v_add_f32_e32 v0, 1.0, v0
	v_rcp_f32_e32 v7, v0
	s_nop 0
	v_pk_mul_f32 v[4:5], v[6:7], v[4:5]
	s_nop 0
	v_pk_mul_f32 v[4:5], v[8:9], v[4:5]
	v_pk_mul_f32 v[6:7], v[10:11], v[34:35] op_sel_hi:[1,0]
	v_cvt_pk_bf16_f32 v3, v4, v5
	v_mov_b32_e32 v104, v2
	v_mov_b32_e32 v105, v3
	s_nop 1
	v_permlane32_swap_b32_e32 v104, v106
	v_permlane32_swap_b32_e32 v105, v107
	ds_write_b128 v120, v[104:107]
	s_waitcnt vmcnt(0)
	v_permlane32_swap_b32_e32 v198, v200
	v_permlane32_swap_b32_e32 v199, v201
	v_mov_b32_e32 v36, v198
	v_mov_b32_e32 v37, v199
	v_mov_b32_e32 v38, v200
	v_mov_b32_e32 v39, v201
	v_lshlrev_b32_e32 v2, 16, v38
	v_mul_f32_e32 v0, 0xbfb8aa3b, v2
	v_exp_f32_e32 v0, v0
	v_and_b32_e32 v3, 0xffff0000, v38
	v_pk_mul_f32 v[8:9], v[12:13], v[34:35] op_sel_hi:[1,0]
	v_add_f32_e32 v0, 1.0, v0
	v_rcp_f32_e32 v4, v0
	v_mul_f32_e32 v0, 0xbfb8aa3b, v3
	v_exp_f32_e32 v0, v0
	s_nop 0
	v_add_f32_e32 v0, 1.0, v0
	v_rcp_f32_e32 v5, v0
	s_nop 0
	v_pk_mul_f32 v[2:3], v[4:5], v[2:3]
	v_lshlrev_b32_e32 v4, 16, v39
	v_mul_f32_e32 v0, 0xbfb8aa3b, v4
	v_exp_f32_e32 v0, v0
	v_and_b32_e32 v5, 0xffff0000, v39
	v_pk_mul_f32 v[2:3], v[6:7], v[2:3]
	v_add_f32_e32 v0, 1.0, v0
	v_rcp_f32_e32 v6, v0
	v_mul_f32_e32 v0, 0xbfb8aa3b, v5
	v_exp_f32_e32 v0, v0
	v_cvt_pk_bf16_f32 v2, v2, v3
	v_add_f32_e32 v0, 1.0, v0
	v_rcp_f32_e32 v7, v0
	s_nop 0
	v_pk_mul_f32 v[4:5], v[6:7], v[4:5]
	s_nop 0
	v_pk_mul_f32 v[4:5], v[8:9], v[4:5]
	v_pk_mul_f32 v[6:7], v[14:15], v[34:35] op_sel_hi:[1,0]
	v_cvt_pk_bf16_f32 v3, v4, v5
	v_mov_b32_e32 v106, v2
	v_mov_b32_e32 v107, v3
	s_waitcnt vmcnt(0)
	v_lshlrev_b32_e32 v2, 16, v36
	v_mul_f32_e32 v0, 0xbfb8aa3b, v2
	v_exp_f32_e32 v0, v0
	v_and_b32_e32 v3, 0xffff0000, v36
	v_pk_mul_f32 v[8:9], v[16:17], v[34:35] op_sel_hi:[1,0]
	v_add_f32_e32 v0, 1.0, v0
	v_rcp_f32_e32 v4, v0
	v_mul_f32_e32 v0, 0xbfb8aa3b, v3
	v_exp_f32_e32 v0, v0
	s_nop 0
	v_add_f32_e32 v0, 1.0, v0
	v_rcp_f32_e32 v5, v0
	s_nop 0
	v_pk_mul_f32 v[2:3], v[4:5], v[2:3]
	v_lshlrev_b32_e32 v4, 16, v37
	v_mul_f32_e32 v0, 0xbfb8aa3b, v4
	v_exp_f32_e32 v0, v0
	v_and_b32_e32 v5, 0xffff0000, v37
	v_pk_mul_f32 v[2:3], v[6:7], v[2:3]
	v_add_f32_e32 v0, 1.0, v0
	v_rcp_f32_e32 v6, v0
	v_mul_f32_e32 v0, 0xbfb8aa3b, v5
	v_exp_f32_e32 v0, v0
	v_cvt_pk_bf16_f32 v2, v2, v3
	v_add_f32_e32 v0, 1.0, v0
	v_rcp_f32_e32 v7, v0
	s_nop 0
	v_pk_mul_f32 v[4:5], v[6:7], v[4:5]
	s_nop 0
	v_pk_mul_f32 v[4:5], v[8:9], v[4:5]
	s_nop 0
	v_cvt_pk_bf16_f32 v3, v4, v5
	v_mov_b32_e32 v104, v2
	v_mov_b32_e32 v105, v3
	s_nop 1
	v_permlane32_swap_b32_e32 v104, v106
	v_permlane32_swap_b32_e32 v105, v107
	ds_write_b128 v121, v[104:107]
	ds_read_b128 v[124:127], v122
	ds_read_b128 v[128:131], v122 offset:1024
	ds_read_b128 v[132:135], v122 offset:2048
	ds_read_b128 v[136:139], v122 offset:3072
	s_waitcnt lgkmcnt(3)
	global_store_dwordx4 v144, v[124:127], s[98:99] offset:768 sc0 sc1
	s_waitcnt lgkmcnt(2)
	global_store_dwordx4 v145, v[128:131], s[98:99] offset:768 sc0 sc1
	s_waitcnt lgkmcnt(1)
	global_store_dwordx4 v146, v[132:135], s[98:99] offset:768 sc0 sc1
	s_waitcnt lgkmcnt(0)
	global_store_dwordx4 v147, v[136:139], s[98:99] offset:768 sc0 sc1

.LBB0_195:
	s_waitcnt vmcnt(0)
	s_barrier
	v_mbcnt_lo_u32_b32 v116, -1, 0
	v_mbcnt_hi_u32_b32 v116, -1, v116
	v_mov_b32_e32 v148, s77
	v_lshlrev_b32_e32 v148, 6, v148
	v_and_b32_e32 v117, 31, v116
	v_lshrrev_b32_e32 v149, 5, v116
	v_lshl_add_u32 v122, v117, 7, v148
	v_and_b32_e32 v117, 7, v117
	v_sub_u32_e32 v118, 1, v149
	v_xor_b32_e32 v118, v118, v117
	v_lshl_add_u32 v118, v118, 4, v122
	v_sub_u32_e32 v119, 3, v149
	v_xor_b32_e32 v119, v119, v117
	v_lshl_add_u32 v119, v119, 4, v122
	v_sub_u32_e32 v120, 5, v149
	v_xor_b32_e32 v120, v120, v117
	v_lshl_add_u32 v120, v120, 4, v122
	v_sub_u32_e32 v121, 7, v149
	v_xor_b32_e32 v121, v121, v117
	v_lshl_add_u32 v121, v121, 4, v122
	v_lshrrev_b32_e32 v117, 3, v116
	v_and_b32_e32 v149, 7, v116
	v_lshl_add_u32 v122, v117, 7, v148
	v_xor_b32_e32 v148, v149, v117
	v_lshl_add_u32 v122, v148, 4, v122
	v_mul_u32_u24_e32 v144, 0x880, v117
	v_lshl_add_u32 v144, v149, 4, v144
	v_add_u32_e32 v145, 0x4400, v144
	v_add_u32_e32 v146, 0x8800, v144
	v_add_u32_e32 v147, 0xcc00, v144
	v_mbcnt_lo_u32_b32 v108, -1, 0
	v_mbcnt_hi_u32_b32 v108, -1, v108
	v_cmp_gt_u32_e32 vcc, 32, v108
	s_nop 1
	v_cndmask_b32_e64 v109, -1, 0, vcc
	v_cndmask_b32_e64 v108, -8, 16, vcc
	v_mbcnt_lo_u32_b32 v68, -1, 0
	v_mbcnt_hi_u32_b32 v68, -1, v68
	s_movk_i32 s0, 0x100
	v_add_u32_e32 v0, s77, v68
	v_mov_b32_e32 v66, s20
	v_mov_b32_e32 v67, s9
	v_cmp_gt_u32_e32 vcc, s0, v0
	v_mov_b32_e32 v69, s21
	v_and_b32_e32 v0, 0xc0, v0
	v_cndmask_b32_e32 v66, v66, v67, vcc
	v_mov_b32_e32 v67, s43
	v_cndmask_b32_e32 v67, v67, v69, vcc
	v_lshl_or_b32 v0, v67, 8, v0
	v_add_u32_e32 v0, s45, v0
	v_and_or_b32 v82, v68, 31, v0
	v_lshlrev_b32_e32 v0, 7, v66
	v_mov_b64_e32 v[66:67], s[74:75]
	v_mad_u64_u32 v[66:67], s[0:1], v82, s4, v[66:67]
	v_lshrrev_b32_e32 v68, 2, v68
	v_and_b32_e32 v70, 8, v68
	v_mov_b32_e32 v71, v1
	v_lshl_add_u64 v[66:67], v[66:67], 0, v[0:1]
	v_lshl_add_u64 v[68:69], v[66:67], 0, v[70:71]
	v_add_co_u32_e32 v66, vcc, s42, v68
	s_mov_b64 s[0:1], 0x4400600
	s_nop 0
	v_addc_co_u32_e32 v67, vcc, 0, v69, vcc
	v_lshl_add_u64 v[76:77], v[68:69], 0, s[0:1]
	v_lshl_add_u64 v[114:115], v[76:77], 0, v[108:109]
	global_load_dwordx4 v[170:173], v[114:115], off nt
	v_mov_b32_e32 v66, v251
	s_nop 1
	v_permlane32_swap_b32_e32 v251, v66
	v_add_f32_e32 v66, v251, v66
	v_rcp_f32_e32 v66, v66
	v_lshl_add_u64 v[80:81], s[74:75], 0, v[0:1]
	v_mad_u64_u32 v[80:81], s[0:1], v82, s33, v[80:81]
	v_pk_mul_f32 v[82:83], v[50:51], v[66:67] op_sel_hi:[1,0]
	v_pk_mul_f32 v[84:85], v[52:53], v[66:67] op_sel_hi:[1,0]
	v_pk_mul_f32 v[86:87], v[54:55], v[66:67] op_sel_hi:[1,0]
	v_pk_mul_f32 v[88:89], v[56:57], v[66:67] op_sel_hi:[1,0]
	v_lshl_add_u64 v[50:51], v[80:81], 0, v[70:71]
	global_load_dwordx4 v[174:177], v[114:115], off offset:32 nt
	global_load_dwordx4 v[178:181], v[114:115], off offset:64 nt
	global_load_dwordx4 v[182:185], v[114:115], off offset:96 nt
	s_mov_b32 s0, 0x4429000
	v_mov_b32_e32 v210, 0x358637bd
	v_mov_b32_e32 v211, 0x3e91f4c4
	v_mov_b32_e32 v212, 0x3c0881c4
	v_mov_b32_e32 v213, 0xbab64f3b
	v_xor_b32_e32 v217, 16, v221
	s_waitcnt vmcnt(3)
	v_permlane32_swap_b32_e32 v170, v172
	v_permlane32_swap_b32_e32 v171, v173
	v_mov_b32_e32 v78, v170
	v_mov_b32_e32 v79, v171
	v_mov_b32_e32 v74, v172
	v_mov_b32_e32 v75, v173
	v_lshlrev_b32_e32 v76, 16, v74
	v_and_b32_e32 v77, 0xffff0000, v74
	v_lshlrev_b32_e32 v74, 16, v75
	v_and_b32_e32 v75, 0xffff0000, v75
	s_waitcnt vmcnt(3)
	v_lshlrev_b32_e32 v90, 16, v78
	v_and_b32_e32 v91, 0xffff0000, v78
	v_lshlrev_b32_e32 v78, 16, v79
	v_and_b32_e32 v79, 0xffff0000, v79
	v_mul_f32_e32 v0, 0xbfb8aa3b, v76
	v_mul_f32_e32 v67, 0xbfb8aa3b, v77
	v_mul_f32_e32 v93, 0xbfb8aa3b, v74
	v_mul_f32_e32 v94, 0xbfb8aa3b, v75
	v_mul_f32_e32 v95, 0xbfb8aa3b, v90
	v_mul_f32_e32 v96, 0xbfb8aa3b, v91
	v_mul_f32_e32 v97, 0xbfb8aa3b, v78
	v_mul_f32_e32 v98, 0xbfb8aa3b, v79
	v_exp_f32_e32 v0, v0
	v_exp_f32_e32 v67, v67
	v_exp_f32_e32 v93, v93
	v_exp_f32_e32 v94, v94
	v_exp_f32_e32 v95, v95
	v_exp_f32_e32 v96, v96
	v_exp_f32_e32 v97, v97
	v_exp_f32_e32 v98, v98
	v_add_f32_e32 v0, 1.0, v0
	v_add_f32_e32 v67, 1.0, v67
	v_add_f32_e32 v93, 1.0, v93
	v_add_f32_e32 v99, 1.0, v94
	v_add_f32_e32 v100, 1.0, v95
	v_add_f32_e32 v101, 1.0, v96
	v_add_f32_e32 v102, 1.0, v97
	v_add_f32_e32 v103, 1.0, v98
	v_rcp_f32_e32 v94, v0
	v_rcp_f32_e32 v95, v67
	v_rcp_f32_e32 v96, v93
	v_rcp_f32_e32 v97, v99
	v_rcp_f32_e32 v98, v100
	v_rcp_f32_e32 v99, v101
	s_waitcnt vmcnt(2)
	v_permlane32_swap_b32_e32 v174, v176
	v_permlane32_swap_b32_e32 v175, v177
	v_mov_b32_e32 v80, v174
	v_mov_b32_e32 v81, v175
	v_mov_b32_e32 v72, v176
	v_mov_b32_e32 v73, v177
	v_lshlrev_b32_e32 v92, 16, v72
	v_rcp_f32_e32 v100, v102
	v_rcp_f32_e32 v101, v103
	v_mul_f32_e32 v0, 0xbfb8aa3b, v92
	v_and_b32_e32 v93, 0xffff0000, v72
	v_exp_f32_e32 v0, v0
	v_mul_f32_e32 v67, 0xbfb8aa3b, v93
	v_pk_mul_f32 v[76:77], v[94:95], v[76:77]
	v_pk_mul_f32 v[74:75], v[96:97], v[74:75]
	v_pk_mul_f32 v[90:91], v[98:99], v[90:91]
	v_exp_f32_e32 v67, v67
	v_pk_mul_f32 v[78:79], v[100:101], v[78:79]
	v_pk_mul_f32 v[76:77], v[82:83], v[76:77]
	v_pk_mul_f32 v[74:75], v[84:85], v[74:75]
	v_pk_mul_f32 v[82:83], v[86:87], v[90:91]
	v_pk_mul_f32 v[78:79], v[88:89], v[78:79]
	v_cvt_pk_bf16_f32 v76, v76, v77
	v_cvt_pk_bf16_f32 v77, v74, v75
	v_cvt_pk_bf16_f32 v74, v82, v83
	v_cvt_pk_bf16_f32 v75, v78, v79
	v_mov_b32_e32 v106, v76
	v_mov_b32_e32 v107, v77
	v_readfirstlane_b32 s98, v50
	v_readfirstlane_b32 s99, v51
	v_mov_b32_e32 v104, v74
	v_mov_b32_e32 v105, v75
	s_nop 1
	v_permlane32_swap_b32_e32 v104, v106
	v_permlane32_swap_b32_e32 v105, v107
	ds_write_b128 v118, v[104:107]
	v_add_f32_e32 v0, 1.0, v0
	v_lshlrev_b32_e32 v74, 16, v73
	v_rcp_f32_e32 v72, v0
	v_pk_mul_f32 v[58:59], v[58:59], v[66:67] op_sel_hi:[1,0]
	v_add_f32_e32 v0, 1.0, v67
	v_and_b32_e32 v75, 0xffff0000, v73
	v_mul_f32_e32 v67, 0xbfb8aa3b, v74
	v_exp_f32_e32 v67, v67
	v_mul_f32_e32 v73, 0xbfb8aa3b, v75
	v_exp_f32_e32 v77, v73
	v_rcp_f32_e32 v73, v0
	v_add_f32_e32 v0, 1.0, v67
	v_rcp_f32_e32 v76, v0
	v_add_f32_e32 v0, 1.0, v77
	v_rcp_f32_e32 v77, v0
	v_pk_mul_f32 v[72:73], v[72:73], v[92:93]
	v_pk_mul_f32 v[60:61], v[60:61], v[66:67] op_sel_hi:[1,0]
	v_pk_mul_f32 v[58:59], v[58:59], v[72:73]
	v_pk_mul_f32 v[72:73], v[76:77], v[74:75]
	v_cvt_pk_bf16_f32 v58, v58, v59
	v_pk_mul_f32 v[60:61], v[60:61], v[72:73]
	s_waitcnt vmcnt(2)
	v_lshlrev_b32_e32 v72, 16, v81
	v_cvt_pk_bf16_f32 v59, v60, v61
	v_mov_b32_e32 v106, v58
	v_mov_b32_e32 v107, v59
	v_lshlrev_b32_e32 v58, 16, v80
	v_mul_f32_e32 v0, 0xbfb8aa3b, v58
	v_and_b32_e32 v59, 0xffff0000, v80
	v_exp_f32_e32 v0, v0
	v_mul_f32_e32 v60, 0xbfb8aa3b, v59
	v_exp_f32_e32 v61, v60
	v_and_b32_e32 v73, 0xffff0000, v81
	v_add_f32_e32 v0, 1.0, v0
	v_rcp_f32_e32 v60, v0
	v_add_f32_e32 v0, 1.0, v61
	v_mul_f32_e32 v61, 0xbfb8aa3b, v72
	v_pk_mul_f32 v[62:63], v[62:63], v[66:67] op_sel_hi:[1,0]
	v_exp_f32_e32 v67, v61
	v_mul_f32_e32 v61, 0xbfb8aa3b, v73
	v_exp_f32_e32 v75, v61
	v_rcp_f32_e32 v61, v0
	v_add_f32_e32 v0, 1.0, v67
	v_rcp_f32_e32 v74, v0
	v_add_f32_e32 v0, 1.0, v75
	v_rcp_f32_e32 v75, v0
	v_pk_mul_f32 v[58:59], v[60:61], v[58:59]
	v_pk_mul_f32 v[60:61], v[64:65], v[66:67] op_sel_hi:[1,0]
	v_pk_mul_f32 v[58:59], v[62:63], v[58:59]
	v_pk_mul_f32 v[62:63], v[74:75], v[72:73]
	v_cvt_pk_bf16_f32 v58, v58, v59
	v_pk_mul_f32 v[60:61], v[60:61], v[62:63]
	s_waitcnt vmcnt(1)
	v_permlane32_swap_b32_e32 v178, v180
	v_permlane32_swap_b32_e32 v179, v181
	v_mov_b32_e32 v56, v178
	v_mov_b32_e32 v57, v179
	v_mov_b32_e32 v70, v180
	v_mov_b32_e32 v71, v181
	v_lshlrev_b32_e32 v62, 16, v71
	v_cvt_pk_bf16_f32 v59, v60, v61
	v_mov_b32_e32 v104, v58
	v_mov_b32_e32 v105, v59
	s_nop 1
	v_permlane32_swap_b32_e32 v104, v106
	v_permlane32_swap_b32_e32 v105, v107
	ds_write_b128 v119, v[104:107]
	v_lshlrev_b32_e32 v58, 16, v70
	v_mul_f32_e32 v0, 0xbfb8aa3b, v58
	v_and_b32_e32 v59, 0xffff0000, v70
	v_exp_f32_e32 v0, v0
	v_mul_f32_e32 v60, 0xbfb8aa3b, v59
	v_exp_f32_e32 v61, v60
	v_and_b32_e32 v63, 0xffff0000, v71
	v_add_f32_e32 v0, 1.0, v0
	v_rcp_f32_e32 v60, v0
	v_add_f32_e32 v0, 1.0, v61
	v_mul_f32_e32 v61, 0xbfb8aa3b, v62
	v_exp_f32_e32 v64, v61
	v_mul_f32_e32 v61, 0xbfb8aa3b, v63
	v_exp_f32_e32 v65, v61
	v_rcp_f32_e32 v61, v0
	v_add_f32_e32 v0, 1.0, v64
	v_rcp_f32_e32 v64, v0
	v_add_f32_e32 v0, 1.0, v65
	v_rcp_f32_e32 v65, v0
	v_pk_mul_f32 v[34:35], v[34:35], v[66:67] op_sel_hi:[1,0]
	v_pk_mul_f32 v[58:59], v[60:61], v[58:59]
	v_pk_mul_f32 v[36:37], v[36:37], v[66:67] op_sel_hi:[1,0]
	v_pk_mul_f32 v[34:35], v[34:35], v[58:59]
	v_pk_mul_f32 v[58:59], v[64:65], v[62:63]
	v_cvt_pk_bf16_f32 v34, v34, v35
	v_pk_mul_f32 v[36:37], v[36:37], v[58:59]
	v_pk_mul_f32 v[38:39], v[38:39], v[66:67] op_sel_hi:[1,0]
	v_cvt_pk_bf16_f32 v35, v36, v37
	v_mov_b32_e32 v106, v34
	v_mov_b32_e32 v107, v35
	s_waitcnt vmcnt(1)
	v_lshlrev_b32_e32 v34, 16, v56
	v_mul_f32_e32 v0, 0xbfb8aa3b, v34
	v_and_b32_e32 v35, 0xffff0000, v56
	v_exp_f32_e32 v0, v0
	v_mul_f32_e32 v36, 0xbfb8aa3b, v35
	v_exp_f32_e32 v37, v36
	v_lshlrev_b32_e32 v56, 16, v57
	v_add_f32_e32 v0, 1.0, v0
	v_rcp_f32_e32 v36, v0
	v_add_f32_e32 v0, 1.0, v37
	v_and_b32_e32 v57, 0xffff0000, v57
	v_mul_f32_e32 v37, 0xbfb8aa3b, v56
	v_exp_f32_e32 v58, v37
	v_mul_f32_e32 v37, 0xbfb8aa3b, v57
	v_exp_f32_e32 v59, v37
	v_rcp_f32_e32 v37, v0
	v_add_f32_e32 v0, 1.0, v58
	v_rcp_f32_e32 v58, v0
	v_add_f32_e32 v0, 1.0, v59
	v_rcp_f32_e32 v59, v0
	v_pk_mul_f32 v[34:35], v[36:37], v[34:35]
	v_pk_mul_f32 v[36:37], v[40:41], v[66:67] op_sel_hi:[1,0]
	v_pk_mul_f32 v[34:35], v[38:39], v[34:35]
	v_pk_mul_f32 v[38:39], v[58:59], v[56:57]
	v_add_co_u32_e32 v60, vcc, s0, v68
	v_pk_mul_f32 v[36:37], v[36:37], v[38:39]
	s_waitcnt vmcnt(0)
	v_permlane32_swap_b32_e32 v182, v184
	v_permlane32_swap_b32_e32 v183, v185
	v_mov_b32_e32 v52, v182
	v_mov_b32_e32 v53, v183
	v_mov_b32_e32 v54, v184
	v_mov_b32_e32 v55, v185
	v_lshlrev_b32_e32 v38, 16, v54
	v_and_b32_e32 v39, 0xffff0000, v54
	v_mul_f32_e32 v0, 0xbfb8aa3b, v38
	v_exp_f32_e32 v0, v0
	v_mul_f32_e32 v40, 0xbfb8aa3b, v39
	v_exp_f32_e32 v41, v40
	v_addc_co_u32_e32 v61, vcc, 0, v69, vcc
	v_add_f32_e32 v0, 1.0, v0
	v_rcp_f32_e32 v40, v0
	v_add_f32_e32 v0, 1.0, v41
	v_rcp_f32_e32 v41, v0
	v_cvt_pk_bf16_f32 v34, v34, v35
	v_cvt_pk_bf16_f32 v35, v36, v37
	v_mov_b32_e32 v104, v34
	v_mov_b32_e32 v105, v35
	s_nop 1
	v_permlane32_swap_b32_e32 v104, v106
	v_permlane32_swap_b32_e32 v105, v107
	ds_write_b128 v120, v[104:107]
	v_pk_mul_f32 v[36:37], v[40:41], v[38:39]
	v_lshlrev_b32_e32 v38, 16, v55
	v_and_b32_e32 v39, 0xffff0000, v55
	v_mul_f32_e32 v0, 0xbfb8aa3b, v38
	v_exp_f32_e32 v0, v0
	v_mul_f32_e32 v40, 0xbfb8aa3b, v39
	v_exp_f32_e32 v40, v40
	v_pk_mul_f32 v[34:35], v[42:43], v[66:67] op_sel_hi:[1,0]
	v_add_f32_e32 v0, 1.0, v0
	v_pk_mul_f32 v[34:35], v[34:35], v[36:37]
	v_rcp_f32_e32 v36, v0
	v_add_f32_e32 v0, 1.0, v40
	v_rcp_f32_e32 v37, v0
	s_mov_b64 s[0:1], 0x4429e00
	v_lshl_add_u64 v[42:43], v[68:69], 0, s[0:1]
	v_pk_mul_f32 v[40:41], v[44:45], v[66:67] op_sel_hi:[1,0]
	v_lshl_add_u64 v[116:117], v[42:43], 0, v[108:109]
	global_load_dwordx4 v[186:189], v[116:117], off nt
	v_pk_mul_f32 v[36:37], v[36:37], v[38:39]
	v_cvt_pk_bf16_f32 v34, v34, v35
	v_pk_mul_f32 v[36:37], v[40:41], v[36:37]
	s_waitcnt vmcnt(1)
	v_lshlrev_b32_e32 v40, 16, v53
	v_cvt_pk_bf16_f32 v35, v36, v37
	v_mov_b32_e32 v106, v34
	v_mov_b32_e32 v107, v35
	v_lshlrev_b32_e32 v34, 16, v52
	v_mul_f32_e32 v0, 0xbfb8aa3b, v34
	v_and_b32_e32 v35, 0xffff0000, v52
	v_exp_f32_e32 v0, v0
	v_mul_f32_e32 v36, 0xbfb8aa3b, v35
	v_exp_f32_e32 v37, v36
	v_and_b32_e32 v41, 0xffff0000, v53
	v_add_f32_e32 v0, 1.0, v0
	v_rcp_f32_e32 v36, v0
	v_add_f32_e32 v0, 1.0, v37
	v_rcp_f32_e32 v37, v0
	v_mul_f32_e32 v0, 0xbfb8aa3b, v40
	v_pk_mul_f32 v[38:39], v[46:47], v[66:67] op_sel_hi:[1,0]
	v_exp_f32_e32 v0, v0
	v_mul_f32_e32 v46, 0xbfb8aa3b, v41
	v_exp_f32_e32 v46, v46
	v_pk_mul_f32 v[34:35], v[36:37], v[34:35]
	v_add_f32_e32 v0, 1.0, v0
	v_rcp_f32_e32 v36, v0
	v_add_f32_e32 v0, 1.0, v46
	v_rcp_f32_e32 v37, v0
	v_pk_mul_f32 v[34:35], v[38:39], v[34:35]
	v_pk_mul_f32 v[38:39], v[48:49], v[66:67] op_sel_hi:[1,0]
	v_cvt_pk_bf16_f32 v34, v34, v35
	v_pk_mul_f32 v[36:37], v[36:37], v[40:41]
	v_mov_b32_e32 v0, v250
	v_pk_mul_f32 v[36:37], v[38:39], v[36:37]
	s_nop 0
	v_permlane32_swap_b32_e32 v250, v0
	v_cvt_pk_bf16_f32 v35, v36, v37
	v_mov_b32_e32 v104, v34
	v_mov_b32_e32 v105, v35
	s_nop 1
	v_permlane32_swap_b32_e32 v104, v106
	v_permlane32_swap_b32_e32 v105, v107
	ds_write_b128 v121, v[104:107]
	ds_read_b128 v[124:127], v122
	ds_read_b128 v[128:131], v122 offset:1024
	ds_read_b128 v[132:135], v122 offset:2048
	ds_read_b128 v[136:139], v122 offset:3072
	s_waitcnt lgkmcnt(3)
	global_store_dwordx4 v144, v[124:127], s[98:99] sc0 sc1
	s_waitcnt lgkmcnt(2)
	global_store_dwordx4 v145, v[128:131], s[98:99] sc0 sc1
	s_waitcnt lgkmcnt(1)
	global_store_dwordx4 v146, v[132:135], s[98:99] sc0 sc1
	s_waitcnt lgkmcnt(0)
	global_store_dwordx4 v147, v[136:139], s[98:99] sc0 sc1
	global_load_dwordx4 v[190:193], v[116:117], off offset:32 nt
	global_load_dwordx4 v[194:197], v[116:117], off offset:64 nt
	s_nop 0
	global_load_dwordx4 v[198:201], v[116:117], off offset:96 nt
	v_add_f32_e32 v0, v250, v0
	v_rcp_f32_e32 v0, v0
	s_mov_b64 s[0:1], 0x11000
	v_pk_mul_f32 v[18:19], v[18:19], v[0:1] op_sel_hi:[1,0]
	v_pk_mul_f32 v[20:21], v[20:21], v[0:1] op_sel_hi:[1,0]
	v_pk_mul_f32 v[22:23], v[22:23], v[0:1] op_sel_hi:[1,0]
	v_pk_mul_f32 v[2:3], v[2:3], v[0:1] op_sel_hi:[1,0]
	v_pk_mul_f32 v[4:5], v[4:5], v[0:1] op_sel_hi:[1,0]
	v_pk_mul_f32 v[6:7], v[6:7], v[0:1] op_sel_hi:[1,0]
	s_waitcnt vmcnt(7)
	v_permlane32_swap_b32_e32 v186, v188
	v_permlane32_swap_b32_e32 v187, v189
	v_mov_b32_e32 v44, v186
	v_mov_b32_e32 v45, v187
	v_mov_b32_e32 v60, v188
	v_mov_b32_e32 v61, v189
	v_lshlrev_b32_e32 v42, 16, v60
	v_mul_f32_e32 v43, 0xbfb8aa3b, v42
	v_exp_f32_e32 v52, v43
	v_and_b32_e32 v43, 0xffff0000, v60
	v_mul_f32_e32 v53, 0xbfb8aa3b, v43
	v_lshlrev_b32_e32 v54, 16, v61
	v_and_b32_e32 v55, 0xffff0000, v61
	v_exp_f32_e32 v53, v53
	v_mul_f32_e32 v56, 0xbfb8aa3b, v54
	v_mul_f32_e32 v57, 0xbfb8aa3b, v55
	v_exp_f32_e32 v56, v56
	v_exp_f32_e32 v57, v57
	v_add_f32_e32 v52, 1.0, v52
	v_add_f32_e32 v53, 1.0, v53
	v_rcp_f32_e32 v52, v52
	v_rcp_f32_e32 v53, v53
	v_add_f32_e32 v56, 1.0, v56
	v_add_f32_e32 v57, 1.0, v57
	v_rcp_f32_e32 v56, v56
	v_rcp_f32_e32 v57, v57
	v_pk_mul_f32 v[42:43], v[52:53], v[42:43]
	s_nop 0
	v_pk_mul_f32 v[18:19], v[18:19], v[42:43]
	v_pk_mul_f32 v[42:43], v[56:57], v[54:55]
	s_nop 0
	v_pk_mul_f32 v[20:21], v[20:21], v[42:43]
	v_cvt_pk_bf16_f32 v42, v18, v19
	v_lshl_add_u64 v[18:19], v[50:51], 0, s[0:1]
	s_mov_b32 s0, 0x11000
	v_cvt_pk_bf16_f32 v43, v20, v21
	v_add_co_u32_e32 v20, vcc, s0, v50
	s_nop 1
	v_addc_co_u32_e32 v21, vcc, 0, v51, vcc
	v_mov_b32_e32 v106, v42
	v_mov_b32_e32 v107, v43
	s_waitcnt vmcnt(7)
	v_lshlrev_b32_e32 v20, 16, v44
	v_mul_f32_e32 v21, 0xbfb8aa3b, v20
	v_exp_f32_e32 v42, v21
	v_and_b32_e32 v21, 0xffff0000, v44
	v_mul_f32_e32 v43, 0xbfb8aa3b, v21
	v_lshlrev_b32_e32 v44, 16, v45
	v_and_b32_e32 v45, 0xffff0000, v45
	v_exp_f32_e32 v43, v43
	v_mul_f32_e32 v50, 0xbfb8aa3b, v44
	v_mul_f32_e32 v51, 0xbfb8aa3b, v45
	v_exp_f32_e32 v50, v50
	v_exp_f32_e32 v51, v51
	v_add_f32_e32 v42, 1.0, v42
	v_add_f32_e32 v43, 1.0, v43
	v_rcp_f32_e32 v42, v42
	v_rcp_f32_e32 v43, v43
	v_add_f32_e32 v50, 1.0, v50
	v_add_f32_e32 v51, 1.0, v51
	v_rcp_f32_e32 v50, v50
	v_rcp_f32_e32 v51, v51
	v_pk_mul_f32 v[20:21], v[42:43], v[20:21]
	s_nop 0
	v_pk_mul_f32 v[20:21], v[22:23], v[20:21]
	v_pk_mul_f32 v[22:23], v[24:25], v[0:1] op_sel_hi:[1,0]
	v_pk_mul_f32 v[24:25], v[50:51], v[44:45]
	v_cvt_pk_bf16_f32 v20, v20, v21
	v_pk_mul_f32 v[22:23], v[22:23], v[24:25]
	v_pk_mul_f32 v[24:25], v[26:27], v[0:1] op_sel_hi:[1,0]
	v_cvt_pk_bf16_f32 v21, v22, v23
	v_readfirstlane_b32 s98, v18
	v_readfirstlane_b32 s99, v19
	v_mov_b32_e32 v104, v20
	v_mov_b32_e32 v105, v21
	s_nop 1
	v_permlane32_swap_b32_e32 v104, v106
	v_permlane32_swap_b32_e32 v105, v107
	ds_write_b128 v118, v[104:107]
	s_waitcnt vmcnt(2)
	v_permlane32_swap_b32_e32 v190, v192
	v_permlane32_swap_b32_e32 v191, v193
	v_mov_b32_e32 v40, v190
	v_mov_b32_e32 v41, v191
	v_mov_b32_e32 v46, v192
	v_mov_b32_e32 v47, v193
	v_lshlrev_b32_e32 v20, 16, v46
	v_mul_f32_e32 v21, 0xbfb8aa3b, v20
	v_exp_f32_e32 v22, v21
	v_and_b32_e32 v21, 0xffff0000, v46
	v_mul_f32_e32 v23, 0xbfb8aa3b, v21
	v_lshlrev_b32_e32 v26, 16, v47
	v_and_b32_e32 v27, 0xffff0000, v47
	v_exp_f32_e32 v23, v23
	v_mul_f32_e32 v42, 0xbfb8aa3b, v26
	v_mul_f32_e32 v43, 0xbfb8aa3b, v27
	v_exp_f32_e32 v42, v42
	v_exp_f32_e32 v43, v43
	v_add_f32_e32 v22, 1.0, v22
	v_add_f32_e32 v23, 1.0, v23
	v_rcp_f32_e32 v22, v22
	v_rcp_f32_e32 v23, v23
	v_add_f32_e32 v42, 1.0, v42
	v_add_f32_e32 v43, 1.0, v43
	v_rcp_f32_e32 v42, v42
	v_rcp_f32_e32 v43, v43
	v_pk_mul_f32 v[20:21], v[22:23], v[20:21]
	v_pk_mul_f32 v[22:23], v[28:29], v[0:1] op_sel_hi:[1,0]
	v_pk_mul_f32 v[20:21], v[24:25], v[20:21]
	v_pk_mul_f32 v[24:25], v[42:43], v[26:27]
	v_cvt_pk_bf16_f32 v20, v20, v21
	v_pk_mul_f32 v[22:23], v[22:23], v[24:25]
	s_waitcnt vmcnt(2)
	v_lshlrev_b32_e32 v26, 16, v41
	v_cvt_pk_bf16_f32 v21, v22, v23
	v_mov_b32_e32 v106, v20
	v_mov_b32_e32 v107, v21
	v_lshlrev_b32_e32 v20, 16, v40
	v_mul_f32_e32 v21, 0xbfb8aa3b, v20
	v_exp_f32_e32 v22, v21
	v_and_b32_e32 v21, 0xffff0000, v40
	v_mul_f32_e32 v23, 0xbfb8aa3b, v21
	v_and_b32_e32 v27, 0xffff0000, v41
	v_exp_f32_e32 v23, v23
	v_mul_f32_e32 v28, 0xbfb8aa3b, v26
	v_mul_f32_e32 v29, 0xbfb8aa3b, v27
	v_exp_f32_e32 v28, v28
	v_exp_f32_e32 v29, v29
	v_add_f32_e32 v22, 1.0, v22
	v_add_f32_e32 v23, 1.0, v23
	v_rcp_f32_e32 v22, v22
	v_rcp_f32_e32 v23, v23
	v_add_f32_e32 v28, 1.0, v28
	v_add_f32_e32 v29, 1.0, v29
	v_rcp_f32_e32 v28, v28
	v_rcp_f32_e32 v29, v29
	v_pk_mul_f32 v[24:25], v[30:31], v[0:1] op_sel_hi:[1,0]
	v_pk_mul_f32 v[20:21], v[22:23], v[20:21]
	v_pk_mul_f32 v[22:23], v[32:33], v[0:1] op_sel_hi:[1,0]
	v_pk_mul_f32 v[20:21], v[24:25], v[20:21]
	v_pk_mul_f32 v[24:25], v[28:29], v[26:27]
	v_cvt_pk_bf16_f32 v20, v20, v21
	v_pk_mul_f32 v[22:23], v[22:23], v[24:25]
	s_waitcnt vmcnt(1)
	v_permlane32_swap_b32_e32 v194, v196
	v_permlane32_swap_b32_e32 v195, v197
	v_mov_b32_e32 v38, v194
	v_mov_b32_e32 v39, v195
	v_mov_b32_e32 v48, v196
	v_mov_b32_e32 v49, v197
	v_lshlrev_b32_e32 v24, 16, v49
	v_cvt_pk_bf16_f32 v21, v22, v23
	v_mov_b32_e32 v104, v20
	v_mov_b32_e32 v105, v21
	s_nop 1
	v_permlane32_swap_b32_e32 v104, v106
	v_permlane32_swap_b32_e32 v105, v107
	ds_write_b128 v119, v[104:107]
	v_lshlrev_b32_e32 v20, 16, v48
	v_mul_f32_e32 v21, 0xbfb8aa3b, v20
	v_exp_f32_e32 v22, v21
	v_and_b32_e32 v21, 0xffff0000, v48
	v_mul_f32_e32 v23, 0xbfb8aa3b, v21
	v_and_b32_e32 v25, 0xffff0000, v49
	v_exp_f32_e32 v23, v23
	v_mul_f32_e32 v26, 0xbfb8aa3b, v24
	v_mul_f32_e32 v27, 0xbfb8aa3b, v25
	v_exp_f32_e32 v26, v26
	v_exp_f32_e32 v27, v27
	v_add_f32_e32 v22, 1.0, v22
	v_add_f32_e32 v23, 1.0, v23
	v_rcp_f32_e32 v22, v22
	v_rcp_f32_e32 v23, v23
	v_add_f32_e32 v26, 1.0, v26
	v_add_f32_e32 v27, 1.0, v27
	v_rcp_f32_e32 v26, v26
	v_rcp_f32_e32 v27, v27
	v_pk_mul_f32 v[20:21], v[22:23], v[20:21]
	s_nop 0
	v_pk_mul_f32 v[2:3], v[2:3], v[20:21]
	v_pk_mul_f32 v[20:21], v[26:27], v[24:25]
	v_cvt_pk_bf16_f32 v2, v2, v3
	v_pk_mul_f32 v[4:5], v[4:5], v[20:21]
	s_waitcnt vmcnt(1)
	v_lshlrev_b32_e32 v20, 16, v39
	v_cvt_pk_bf16_f32 v3, v4, v5
	v_mov_b32_e32 v106, v2
	v_mov_b32_e32 v107, v3
	v_lshlrev_b32_e32 v2, 16, v38
	v_mul_f32_e32 v3, 0xbfb8aa3b, v2
	v_exp_f32_e32 v4, v3
	v_and_b32_e32 v3, 0xffff0000, v38
	v_mul_f32_e32 v5, 0xbfb8aa3b, v3
	v_and_b32_e32 v21, 0xffff0000, v39
	v_exp_f32_e32 v5, v5
	v_mul_f32_e32 v22, 0xbfb8aa3b, v20
	v_mul_f32_e32 v23, 0xbfb8aa3b, v21
	v_exp_f32_e32 v22, v22
	v_exp_f32_e32 v23, v23
	v_add_f32_e32 v4, 1.0, v4
	v_add_f32_e32 v5, 1.0, v5
	v_rcp_f32_e32 v4, v4
	v_rcp_f32_e32 v5, v5
	v_add_f32_e32 v22, 1.0, v22
	v_add_f32_e32 v23, 1.0, v23
	v_rcp_f32_e32 v22, v22
	v_rcp_f32_e32 v23, v23
	v_pk_mul_f32 v[2:3], v[4:5], v[2:3]
	v_pk_mul_f32 v[4:5], v[8:9], v[0:1] op_sel_hi:[1,0]
	v_pk_mul_f32 v[2:3], v[6:7], v[2:3]
	v_pk_mul_f32 v[6:7], v[22:23], v[20:21]
	v_cvt_pk_bf16_f32 v2, v2, v3
	v_pk_mul_f32 v[4:5], v[4:5], v[6:7]
	s_waitcnt vmcnt(0)
	v_permlane32_swap_b32_e32 v198, v200
	v_permlane32_swap_b32_e32 v199, v201
	v_mov_b32_e32 v34, v198
	v_mov_b32_e32 v35, v199
	v_mov_b32_e32 v36, v200
	v_mov_b32_e32 v37, v201
	v_lshlrev_b32_e32 v8, 16, v37
	v_cvt_pk_bf16_f32 v3, v4, v5
	v_mov_b32_e32 v104, v2
	v_mov_b32_e32 v105, v3
	s_nop 1
	v_permlane32_swap_b32_e32 v104, v106
	v_permlane32_swap_b32_e32 v105, v107
	ds_write_b128 v120, v[104:107]
	v_lshlrev_b32_e32 v2, 16, v36
	v_mul_f32_e32 v3, 0xbfb8aa3b, v2
	v_exp_f32_e32 v4, v3
	v_and_b32_e32 v3, 0xffff0000, v36
	v_mul_f32_e32 v5, 0xbfb8aa3b, v3
	v_and_b32_e32 v9, 0xffff0000, v37
	v_exp_f32_e32 v5, v5
	v_pk_mul_f32 v[6:7], v[10:11], v[0:1] op_sel_hi:[1,0]
	v_mul_f32_e32 v10, 0xbfb8aa3b, v8
	v_mul_f32_e32 v11, 0xbfb8aa3b, v9
	v_exp_f32_e32 v10, v10
	v_exp_f32_e32 v11, v11
	v_add_f32_e32 v4, 1.0, v4
	v_add_f32_e32 v5, 1.0, v5
	v_rcp_f32_e32 v4, v4
	v_rcp_f32_e32 v5, v5
	v_add_f32_e32 v10, 1.0, v10
	v_add_f32_e32 v11, 1.0, v11
	v_rcp_f32_e32 v10, v10
	v_rcp_f32_e32 v11, v11
	v_pk_mul_f32 v[2:3], v[4:5], v[2:3]
	v_pk_mul_f32 v[4:5], v[12:13], v[0:1] op_sel_hi:[1,0]
	v_pk_mul_f32 v[2:3], v[6:7], v[2:3]
	v_pk_mul_f32 v[6:7], v[10:11], v[8:9]
	v_cvt_pk_bf16_f32 v2, v2, v3
	v_pk_mul_f32 v[4:5], v[4:5], v[6:7]
	s_waitcnt vmcnt(0)
	v_lshlrev_b32_e32 v8, 16, v35
	v_cvt_pk_bf16_f32 v3, v4, v5
	v_mov_b32_e32 v106, v2
	v_mov_b32_e32 v107, v3
	v_lshlrev_b32_e32 v2, 16, v34
	v_mul_f32_e32 v3, 0xbfb8aa3b, v2
	v_exp_f32_e32 v4, v3
	v_and_b32_e32 v3, 0xffff0000, v34
	v_mul_f32_e32 v5, 0xbfb8aa3b, v3
	v_and_b32_e32 v9, 0xffff0000, v35
	v_exp_f32_e32 v5, v5
	v_mul_f32_e32 v10, 0xbfb8aa3b, v8
	v_mul_f32_e32 v11, 0xbfb8aa3b, v9
	v_exp_f32_e32 v10, v10
	v_exp_f32_e32 v11, v11
	v_add_f32_e32 v4, 1.0, v4
	v_add_f32_e32 v5, 1.0, v5
	v_rcp_f32_e32 v4, v4
	v_rcp_f32_e32 v5, v5
	v_add_f32_e32 v10, 1.0, v10
	v_add_f32_e32 v11, 1.0, v11
	v_rcp_f32_e32 v10, v10
	v_rcp_f32_e32 v11, v11
	v_pk_mul_f32 v[6:7], v[14:15], v[0:1] op_sel_hi:[1,0]
	v_pk_mul_f32 v[2:3], v[4:5], v[2:3]
	v_pk_mul_f32 v[4:5], v[16:17], v[0:1] op_sel_hi:[1,0]
	v_pk_mul_f32 v[2:3], v[6:7], v[2:3]
	v_pk_mul_f32 v[6:7], v[10:11], v[8:9]
	v_cvt_pk_bf16_f32 v2, v2, v3
	v_pk_mul_f32 v[4:5], v[4:5], v[6:7]
	s_nop 0
	v_cvt_pk_bf16_f32 v3, v4, v5
	v_mov_b32_e32 v104, v2
	v_mov_b32_e32 v105, v3
	s_nop 1
	v_permlane32_swap_b32_e32 v104, v106
	v_permlane32_swap_b32_e32 v105, v107
	ds_write_b128 v121, v[104:107]
	ds_read_b128 v[124:127], v122
	ds_read_b128 v[128:131], v122 offset:1024
	ds_read_b128 v[132:135], v122 offset:2048
	ds_read_b128 v[136:139], v122 offset:3072
	s_waitcnt lgkmcnt(3)
	global_store_dwordx4 v144, v[124:127], s[98:99] sc0 sc1
	s_waitcnt lgkmcnt(2)
	global_store_dwordx4 v145, v[128:131], s[98:99] sc0 sc1
	s_waitcnt lgkmcnt(1)
	global_store_dwordx4 v146, v[132:135], s[98:99] sc0 sc1
	s_waitcnt lgkmcnt(0)
	global_store_dwordx4 v147, v[136:139], s[98:99] sc0 sc1
